# prologue/epilogue de-serialisation stack: attention epilogue sub-LN gain loads issued together up front (no per-store wait), K/V DMA offset increments on the scalar unit, s_setprio 0 after the end-of-
# speedup vs baseline: 1.0261x; 1.0039x over previous
; #define PG8_STAGE(bufoff, gbase, voff) do { _Pragma("unroll") for (int _i = 0; _i < 2; ++_i) \
;         __builtin_amdgcn_global_load_lds((const unsigned*)((const char*)(gbase) + (voff)[_i]), (PG8_LAS unsigned*)(lds + (bufoff) + ldsw + _i * 8192), 16, 0, 0); } while (0)
; #define PG8_LDA(dst, b, h) do { _Pragma("unroll") for (int m = 0; m < 4; ++m) _Pragma("unroll") for (int k = 0; k < 2; ++k) dst[m][k] = *(const PG8_LAS bf16x8*)(lds + PG8_SA(b, h) + aoff + m * 2048 + k * 1024); } while (0)
; #define PG8_LDB(dst, b, h) do { _Pragma("unroll") for (int n = 0; n < 2; ++n) _Pragma("unroll") for (int k = 0; k < 2; ++k) dst[n][k] = *(const PG8_LAS bf16x8*)(lds + PG8_SB(b, h) + boff + n * 2048 + k * 1024); } while (0)
; #define PG8_MMA(ai, bj, At, Bt) do { __builtin_amdgcn_s_setprio(1); _Pragma("unroll") for (int m = 0; m < 4; ++m) _Pragma("unroll") for (int n = 0; n < 2; ++n) _Pragma("unroll") for (int k = 0; k < 2; ++k) \
;         acc[ai][bj][m][n] = __builtin_amdgcn_mfma_f32_16x16x32_bf16(Bt[n][k], At[m][k], acc[ai][bj][m][n], 0, 0, 0); __builtin_amdgcn_s_setprio(0); } while (0)
; #define PG8_WAIT_V(n) asm volatile("s_waitcnt vmcnt(" #n ")" ::: "memory")
; #define PG8_BAR __builtin_amdgcn_s_barrier()
; template <class Epi, class Sched, bool ALIGN_EPI = false, bool SP2 = false>
; __device__ __forceinline__ void gemm_phase(PG8_LAS unsigned char* lds, const Gemm g, const Sched& S, const Epi& E, int wid0) {
;     ...
;         for (int t = 0; t < nt; t += 2) {
;             const bool last = (t == nt - 2);
;             const char* a1 = cA + (size_t)(t + 1) * kstep;
;             const char* a2 = last ? nA : cA + (size_t)(t + 2) * kstep; const char* b2 = last ? nB : cB + (size_t)(t + 2) * kstep;
;             const char* a3 = a2 + kstep; const char* b3 = b2 + kstep;
;             if (last && has_next) S.a_ready(nxt);
;             if constexpr (SP2) {
;             PG8_LDB(B0, 0, 0); PG8_LDB(B1, 0, 1); PG8_SCHED; PG8_LDA(At, 0, 0); PG8_STAGE(PG8_SA(1, 1), a1 + hstep, voffA);
;             PG8_WAIT_V(8); PG8_WAIT_L(0); PG8_BAR; PG8_MMA(0, 0, At, B0); PG8_MMA(0, 1, At, B1); PG8_BAR; PG8_SCHED;
;             PG8_LDA(At, 0, 1); PG8_STAGE(PG8_SB(0, 0), b2, voffB); PG8_STAGE(PG8_SB(0, 1), b2 + hstep, voffB); PG8_STAGE(PG8_SA(0, 0), a2, voffA);
;             PG8_WAIT_V(8); PG8_WAIT_L(0); PG8_BAR; PG8_MMA(1, 0, At, B0); PG8_MMA(1, 1, At, B1); PG8_BAR; PG8_SCHED;
.LBB0_143:
	s_add_u32 s26, s84, 0xfffc0080
	s_addc_u32 s27, s85, -1
	s_add_i32 s65, 0, 0x10000
	s_cmp_eq_u32 s64, 12
	s_cselect_b32 vcc_hi, s45, s27
	s_cselect_b32 vcc_lo, s77, s26
	s_cselect_b32 s87, s75, s11
	s_cselect_b32 s86, s83, s10
	s_add_i32 s66, 0, 0x14000
	v_add_u32_e32 v140, s65, v164
	v_add_u32_e32 v162, s66, v164
	ds_read_b128 v[128:131], v140
	ds_read_b128 v[132:135], v140 offset:1024
	ds_read_b128 v[136:139], v140 offset:2048
	ds_read_b128 v[140:143], v140 offset:3072
	ds_read_b128 v[158:161], v162
	ds_read_b128 v[166:169], v162 offset:1024
	ds_read_b128 v[170:173], v162 offset:2048
	ds_read_b128 v[174:177], v162 offset:3072
	v_lshl_add_u64 v[162:163], s[84:85], 0, v[156:157]
	s_add_i32 m0, s94, 0xc000
	ds_read_b128 v[178:181], v165
	ds_read_b128 v[182:185], v165 offset:1024
	ds_read_b128 v[186:189], v165 offset:2048
	ds_read_b128 v[198:201], v165 offset:3072
	ds_read_b128 v[202:205], v165 offset:4096
	ds_read_b128 v[206:209], v165 offset:5120
	ds_read_b128 v[210:213], v165 offset:6144
	ds_read_b128 v[220:223], v165 offset:7168
	global_load_lds_dwordx4 v[162:163], off
	v_lshl_add_u64 v[162:163], s[84:85], 0, v[154:155]
	s_add_i32 m0, s94, 0xe000
	s_nop 0
	global_load_lds_dwordx4 v[162:163], off
	s_waitcnt vmcnt(8)
	s_waitcnt lgkmcnt(0)
	s_barrier
	s_setprio 1
	s_waitcnt lgkmcnt(0)
	v_mfma_f32_16x16x32_bf16 v[124:127], v[128:131], v[178:181], v[124:127]
	v_mfma_f32_16x16x32_bf16 v[120:123], v[136:139], v[178:181], v[120:123]
	v_mfma_f32_16x16x32_bf16 v[108:111], v[128:131], v[186:189], v[108:111]
	v_mfma_f32_16x16x32_bf16 v[104:107], v[136:139], v[186:189], v[104:107]
	v_mfma_f32_16x16x32_bf16 v[92:95], v[128:131], v[202:205], v[92:95]
	v_mfma_f32_16x16x32_bf16 v[88:91], v[136:139], v[202:205], v[88:91]
	v_mfma_f32_16x16x32_bf16 v[76:79], v[128:131], v[210:213], v[76:79]
	v_mfma_f32_16x16x32_bf16 v[72:75], v[136:139], v[210:213], v[72:75]
	v_mfma_f32_16x16x32_bf16 v[124:127], v[132:135], v[182:185], v[124:127]
	v_mfma_f32_16x16x32_bf16 v[120:123], v[140:143], v[182:185], v[120:123]
	v_mfma_f32_16x16x32_bf16 v[108:111], v[132:135], v[198:201], v[108:111]
	v_mfma_f32_16x16x32_bf16 v[104:107], v[140:143], v[198:201], v[104:107]
	v_mfma_f32_16x16x32_bf16 v[92:95], v[132:135], v[206:209], v[92:95]
	v_mfma_f32_16x16x32_bf16 v[88:91], v[140:143], v[206:209], v[88:91]
	v_mfma_f32_16x16x32_bf16 v[76:79], v[132:135], v[220:223], v[76:79]
	v_mfma_f32_16x16x32_bf16 v[72:75], v[140:143], v[220:223], v[72:75]
	s_setprio 0
	s_setprio 1
	v_mfma_f32_16x16x32_bf16 v[116:119], v[158:161], v[178:181], v[116:119]
	v_mfma_f32_16x16x32_bf16 v[112:115], v[170:173], v[178:181], v[112:115]
	v_mfma_f32_16x16x32_bf16 v[100:103], v[158:161], v[186:189], v[100:103]
	v_mfma_f32_16x16x32_bf16 v[96:99], v[170:173], v[186:189], v[96:99]
	v_mfma_f32_16x16x32_bf16 v[84:87], v[158:161], v[202:205], v[84:87]
	v_mfma_f32_16x16x32_bf16 v[80:83], v[170:173], v[202:205], v[80:83]
	v_mfma_f32_16x16x32_bf16 v[68:71], v[158:161], v[210:213], v[68:71]
	v_mfma_f32_16x16x32_bf16 v[64:67], v[170:173], v[210:213], v[64:67]
	v_mfma_f32_16x16x32_bf16 v[116:119], v[166:169], v[182:185], v[116:119]
	v_mfma_f32_16x16x32_bf16 v[112:115], v[174:177], v[182:185], v[112:115]
	v_mfma_f32_16x16x32_bf16 v[100:103], v[166:169], v[198:201], v[100:103]
	v_mfma_f32_16x16x32_bf16 v[96:99], v[174:177], v[198:201], v[96:99]
	v_mfma_f32_16x16x32_bf16 v[84:87], v[166:169], v[206:209], v[84:87]
	v_mfma_f32_16x16x32_bf16 v[80:83], v[174:177], v[206:209], v[80:83]
	v_mfma_f32_16x16x32_bf16 v[68:71], v[166:169], v[220:223], v[68:71]
	v_mfma_f32_16x16x32_bf16 v[64:67], v[174:177], v[220:223], v[64:67]
	s_barrier
	s_setprio 0
	s_add_i32 s26, s65, s93
	v_lshl_add_u64 v[162:163], s[86:87], 0, v[148:149]
	s_mov_b32 m0, s26
	ds_read_b128 v[178:181], v165 offset:16384
	ds_read_b128 v[182:185], v165 offset:17408
	ds_read_b128 v[186:189], v165 offset:18432
	ds_read_b128 v[198:201], v165 offset:19456
	ds_read_b128 v[202:205], v165 offset:20480
	ds_read_b128 v[206:209], v165 offset:21504
	ds_read_b128 v[210:213], v165 offset:22528
	ds_read_b128 v[220:223], v165 offset:23552
	global_load_lds_dwordx4 v[162:163], off
	s_add_i32 m0, s26, 0x2000
	s_add_u32 s26, s86, 0x40000
	v_lshl_add_u64 v[190:191], s[86:87], 0, v[144:145]
	s_addc_u32 s27, s87, 0
	s_add_i32 s65, s66, s93
	global_load_lds_dwordx4 v[190:191], off
	v_lshl_add_u64 v[194:195], s[26:27], 0, v[148:149]
	s_mov_b32 m0, s65
	v_lshl_add_u64 v[196:197], vcc, 0, v[146:147]
	global_load_lds_dwordx4 v[194:195], off
	v_lshl_add_u64 v[194:195], s[26:27], 0, v[144:145]
	s_add_i32 m0, s65, 0x2000
	s_nop 0
	global_load_lds_dwordx4 v[194:195], off
	v_lshl_add_u64 v[194:195], vcc, 0, v[150:151]
	s_mov_b32 m0, s94
	s_nop 0
	global_load_lds_dwordx4 v[194:195], off
	s_mov_b32 m0, s95
	s_nop 0
	global_load_lds_dwordx4 v[196:197], off
	s_waitcnt vmcnt(8)
	s_waitcnt lgkmcnt(0)
	s_barrier
; #define PG8_STAGE(bufoff, gbase, voff) do { _Pragma("unroll") for (int _i = 0; _i < 2; ++_i) \
;         __builtin_amdgcn_global_load_lds((const unsigned*)((const char*)(gbase) + (voff)[_i]), (PG8_LAS unsigned*)(lds + (bufoff) + ldsw + _i * 8192), 16, 0, 0); } while (0)
; #define PG8_LDA(dst, b, h) do { _Pragma("unroll") for (int m = 0; m < 4; ++m) _Pragma("unroll") for (int k = 0; k < 2; ++k) dst[m][k] = *(const PG8_LAS bf16x8*)(lds + PG8_SA(b, h) + aoff + m * 2048 + k * 1024); } while (0)
; #define PG8_LDB(dst, b, h) do { _Pragma("unroll") for (int n = 0; n < 2; ++n) _Pragma("unroll") for (int k = 0; k < 2; ++k) dst[n][k] = *(const PG8_LAS bf16x8*)(lds + PG8_SB(b, h) + boff + n * 2048 + k * 1024); } while (0)
; #define PG8_MMA(ai, bj, At, Bt) do { __builtin_amdgcn_s_setprio(1); _Pragma("unroll") for (int m = 0; m < 4; ++m) _Pragma("unroll") for (int n = 0; n < 2; ++n) _Pragma("unroll") for (int k = 0; k < 2; ++k) \
;         acc[ai][bj][m][n] = __builtin_amdgcn_mfma_f32_16x16x32_bf16(Bt[n][k], At[m][k], acc[ai][bj][m][n], 0, 0, 0); __builtin_amdgcn_s_setprio(0); } while (0)
; #define PG8_WAIT_V(n) asm volatile("s_waitcnt vmcnt(" #n ")" ::: "memory")
; #define PG8_WAIT_L(n) asm volatile("s_waitcnt lgkmcnt(" #n ")" ::: "memory")
; #define PG8_BAR __builtin_amdgcn_s_barrier()
; #define PG8_SCHED __builtin_amdgcn_sched_barrier(0)
; template <class Epi, class Sched, bool ALIGN_EPI = false, bool SP2 = false>
; __device__ __forceinline__ void gemm_phase(PG8_LAS unsigned char* lds, const Gemm g, const Sched& S, const Epi& E, int wid0) {
;     ...
;             PG8_WAIT_V(8); PG8_WAIT_L(0); PG8_BAR; PG8_MMA(1, 0, At, B0); PG8_MMA(1, 1, At, B1); PG8_BAR; PG8_SCHED;
;             PG8_LDB(B0, 1, 0); PG8_LDB(B1, 1, 1); PG8_SCHED; PG8_LDA(At, 1, 0); PG8_STAGE(PG8_SA(0, 1), a2 + hstep, voffA);
;             PG8_WAIT_V(8); PG8_WAIT_L(0); PG8_BAR; PG8_MMA(0, 0, At, B0); PG8_MMA(0, 1, At, B1); PG8_BAR; PG8_SCHED;
	s_setprio 1
	s_waitcnt lgkmcnt(0)
	v_mfma_f32_16x16x32_bf16 v[60:63], v[128:131], v[178:181], v[60:63]
	v_mfma_f32_16x16x32_bf16 v[56:59], v[136:139], v[178:181], v[56:59]
	v_mfma_f32_16x16x32_bf16 v[44:47], v[128:131], v[186:189], v[44:47]
	v_mfma_f32_16x16x32_bf16 v[40:43], v[136:139], v[186:189], v[40:43]
	v_mfma_f32_16x16x32_bf16 v[28:31], v[128:131], v[202:205], v[28:31]
	v_mfma_f32_16x16x32_bf16 v[24:27], v[136:139], v[202:205], v[24:27]
	v_mfma_f32_16x16x32_bf16 v[12:15], v[128:131], v[210:213], v[12:15]
	v_mfma_f32_16x16x32_bf16 v[8:11], v[136:139], v[210:213], v[8:11]
	v_mfma_f32_16x16x32_bf16 v[60:63], v[132:135], v[182:185], v[60:63]
	v_mfma_f32_16x16x32_bf16 v[56:59], v[140:143], v[182:185], v[56:59]
	v_mfma_f32_16x16x32_bf16 v[44:47], v[132:135], v[198:201], v[44:47]
	v_mfma_f32_16x16x32_bf16 v[40:43], v[140:143], v[198:201], v[40:43]
	v_mfma_f32_16x16x32_bf16 v[28:31], v[132:135], v[206:209], v[28:31]
	v_mfma_f32_16x16x32_bf16 v[24:27], v[140:143], v[206:209], v[24:27]
	v_mfma_f32_16x16x32_bf16 v[12:15], v[132:135], v[220:223], v[12:15]
	v_mfma_f32_16x16x32_bf16 v[8:11], v[140:143], v[220:223], v[8:11]
	s_setprio 0
	s_setprio 1
	v_mfma_f32_16x16x32_bf16 v[52:55], v[158:161], v[178:181], v[52:55]
	v_mfma_f32_16x16x32_bf16 v[48:51], v[170:173], v[178:181], v[48:51]
	v_mfma_f32_16x16x32_bf16 v[36:39], v[158:161], v[186:189], v[36:39]
	v_mfma_f32_16x16x32_bf16 v[32:35], v[170:173], v[186:189], v[32:35]
	v_mfma_f32_16x16x32_bf16 v[20:23], v[158:161], v[202:205], v[20:23]
	v_mfma_f32_16x16x32_bf16 v[16:19], v[170:173], v[202:205], v[16:19]
	v_mfma_f32_16x16x32_bf16 v[4:7], v[158:161], v[210:213], v[4:7]
	v_mfma_f32_16x16x32_bf16 v[0:3], v[170:173], v[210:213], v[0:3]
	v_mfma_f32_16x16x32_bf16 v[52:55], v[166:169], v[182:185], v[52:55]
	v_mfma_f32_16x16x32_bf16 v[48:51], v[174:177], v[182:185], v[48:51]
	v_mfma_f32_16x16x32_bf16 v[36:39], v[166:169], v[198:201], v[36:39]
	v_mfma_f32_16x16x32_bf16 v[32:35], v[174:177], v[198:201], v[32:35]
	v_mfma_f32_16x16x32_bf16 v[20:23], v[166:169], v[206:209], v[20:23]
	v_mfma_f32_16x16x32_bf16 v[16:19], v[174:177], v[206:209], v[16:19]
	v_mfma_f32_16x16x32_bf16 v[4:7], v[166:169], v[220:223], v[4:7]
	v_mfma_f32_16x16x32_bf16 v[0:3], v[174:177], v[220:223], v[0:3]
	s_barrier
	s_setprio 0
	s_add_i32 s65, 0, 0x18000
	s_add_i32 s66, 0, 0x1c000
	v_add_u32_e32 v140, s65, v164
	v_add_u32_e32 v174, s66, v164
	ds_read_b128 v[128:131], v140
	ds_read_b128 v[132:135], v140 offset:1024
	ds_read_b128 v[136:139], v140 offset:2048
	ds_read_b128 v[140:143], v140 offset:3072
	ds_read_b128 v[158:161], v174
	ds_read_b128 v[166:169], v174 offset:1024
	ds_read_b128 v[170:173], v174 offset:2048
	ds_read_b128 v[174:177], v174 offset:3072
	s_add_u32 s26, vcc_lo, 0x40000
	s_addc_u32 s27, vcc_hi, 0
	s_mov_b32 m0, s96
	v_lshl_add_u64 v[214:215], s[26:27], 0, v[150:151]
	ds_read_b128 v[178:181], v165 offset:32768
	ds_read_b128 v[182:185], v165 offset:33792
	ds_read_b128 v[186:189], v165 offset:34816
	ds_read_b128 v[198:201], v165 offset:35840
	ds_read_b128 v[202:205], v165 offset:36864
	ds_read_b128 v[206:209], v165 offset:37888
	ds_read_b128 v[210:213], v165 offset:38912
	ds_read_b128 v[220:223], v165 offset:39936
	global_load_lds_dwordx4 v[214:215], off
	v_lshl_add_u64 v[214:215], s[26:27], 0, v[146:147]
	s_mov_b32 m0, s97
	s_nop 0
	global_load_lds_dwordx4 v[214:215], off
	s_waitcnt vmcnt(8)
	s_waitcnt lgkmcnt(0)
	s_barrier
	s_setprio 1
	s_waitcnt lgkmcnt(0)
	v_mfma_f32_16x16x32_bf16 v[124:127], v[128:131], v[178:181], v[124:127]
	v_mfma_f32_16x16x32_bf16 v[120:123], v[136:139], v[178:181], v[120:123]
	v_mfma_f32_16x16x32_bf16 v[108:111], v[128:131], v[186:189], v[108:111]
	v_mfma_f32_16x16x32_bf16 v[104:107], v[136:139], v[186:189], v[104:107]
	v_mfma_f32_16x16x32_bf16 v[92:95], v[128:131], v[202:205], v[92:95]
	v_mfma_f32_16x16x32_bf16 v[88:91], v[136:139], v[202:205], v[88:91]
	v_mfma_f32_16x16x32_bf16 v[76:79], v[128:131], v[210:213], v[76:79]
	v_mfma_f32_16x16x32_bf16 v[72:75], v[136:139], v[210:213], v[72:75]
	v_mfma_f32_16x16x32_bf16 v[124:127], v[132:135], v[182:185], v[124:127]
	v_mfma_f32_16x16x32_bf16 v[120:123], v[140:143], v[182:185], v[120:123]
	v_mfma_f32_16x16x32_bf16 v[108:111], v[132:135], v[198:201], v[108:111]
	v_mfma_f32_16x16x32_bf16 v[104:107], v[140:143], v[198:201], v[104:107]
	v_mfma_f32_16x16x32_bf16 v[92:95], v[132:135], v[206:209], v[92:95]
	v_mfma_f32_16x16x32_bf16 v[88:91], v[140:143], v[206:209], v[88:91]
	v_mfma_f32_16x16x32_bf16 v[76:79], v[132:135], v[220:223], v[76:79]
	v_mfma_f32_16x16x32_bf16 v[72:75], v[140:143], v[220:223], v[72:75]
	s_setprio 0
	s_setprio 1
	v_mfma_f32_16x16x32_bf16 v[116:119], v[158:161], v[178:181], v[116:119]
	v_mfma_f32_16x16x32_bf16 v[112:115], v[170:173], v[178:181], v[112:115]
	v_mfma_f32_16x16x32_bf16 v[100:103], v[158:161], v[186:189], v[100:103]
	v_mfma_f32_16x16x32_bf16 v[96:99], v[170:173], v[186:189], v[96:99]
	v_mfma_f32_16x16x32_bf16 v[84:87], v[158:161], v[202:205], v[84:87]
	v_mfma_f32_16x16x32_bf16 v[80:83], v[170:173], v[202:205], v[80:83]
	v_mfma_f32_16x16x32_bf16 v[68:71], v[158:161], v[210:213], v[68:71]
	v_mfma_f32_16x16x32_bf16 v[64:67], v[170:173], v[210:213], v[64:67]
	v_mfma_f32_16x16x32_bf16 v[116:119], v[166:169], v[182:185], v[116:119]
	v_mfma_f32_16x16x32_bf16 v[112:115], v[174:177], v[182:185], v[112:115]
	v_mfma_f32_16x16x32_bf16 v[100:103], v[166:169], v[198:201], v[100:103]
	v_mfma_f32_16x16x32_bf16 v[96:99], v[174:177], v[198:201], v[96:99]
	v_mfma_f32_16x16x32_bf16 v[84:87], v[166:169], v[206:209], v[84:87]
	v_mfma_f32_16x16x32_bf16 v[80:83], v[174:177], v[206:209], v[80:83]
	v_mfma_f32_16x16x32_bf16 v[68:71], v[166:169], v[220:223], v[68:71]
	v_mfma_f32_16x16x32_bf16 v[64:67], v[174:177], v[220:223], v[64:67]
	s_barrier
; #define PG8_STAGE(bufoff, gbase, voff) do { _Pragma("unroll") for (int _i = 0; _i < 2; ++_i) \
;         __builtin_amdgcn_global_load_lds((const unsigned*)((const char*)(gbase) + (voff)[_i]), (PG8_LAS unsigned*)(lds + (bufoff) + ldsw + _i * 8192), 16, 0, 0); } while (0)
; #define PG8_LDA(dst, b, h) do { _Pragma("unroll") for (int m = 0; m < 4; ++m) _Pragma("unroll") for (int k = 0; k < 2; ++k) dst[m][k] = *(const PG8_LAS bf16x8*)(lds + PG8_SA(b, h) + aoff + m * 2048 + k * 1024); } while (0)
; #define PG8_BAR __builtin_amdgcn_s_barrier()
; template <class Epi, class Sched, bool ALIGN_EPI = false, bool SP2 = false>
; __device__ __forceinline__ void gemm_phase(PG8_LAS unsigned char* lds, const Gemm g, const Sched& S, const Epi& E, int wid0) {
;     ...
;             PG8_LDA(At, 1, 1); PG8_STAGE(PG8_SB(1, 0), b3, voffB); PG8_STAGE(PG8_SB(1, 1), b3 + hstep, voffB); PG8_STAGE(PG8_SA(1, 0), a3, voffA);
;             PG8_WAIT_V(8); PG8_WAIT_L(0); PG8_BAR; PG8_MMA(1, 0, At, B0); PG8_MMA(1, 1, At, B1); PG8_BAR; PG8_SCHED;
;             } else {
;             PG8_LDB(B0, 0, 0); PG8_SCHED; PG8_LDA(At, 0, 0); PG8_STAGE(PG8_SA(1, 1), a1 + hstep, voffA);
;             PG8_WAIT_L(8); PG8_BAR; PG8_WAIT_L(0); PG8_MMA(0, 0, At, B0); PG8_BAR; PG8_SCHED;
;             PG8_LDB(B1, 0, 1); PG8_STAGE(PG8_SB(0, 0), b2, voffB);
;             PG8_BAR; PG8_WAIT_L(0); PG8_MMA(0, 1, At, B1); PG8_BAR;
;             PG8_LDA(At, 0, 1); PG8_STAGE(PG8_SA(0, 0), a2, voffA);
;             PG8_BAR; PG8_WAIT_L(0); PG8_MMA(1, 0, At, B0); PG8_BAR; PG8_SCHED;
;             PG8_STAGE(PG8_SB(0, 1), b2 + hstep, voffB);
;             PG8_WAIT_V(6); PG8_BAR; PG8_MMA(1, 1, At, B1); PG8_BAR;
;             PG8_LDB(B0, 1, 0); PG8_SCHED; PG8_LDA(At, 1, 0); PG8_STAGE(PG8_SA(0, 1), a2 + hstep, voffA);
;             PG8_WAIT_L(8); PG8_BAR; PG8_WAIT_L(0); PG8_MMA(0, 0, At, B0); PG8_BAR; PG8_SCHED;
;             PG8_LDB(B1, 1, 1); PG8_STAGE(PG8_SB(1, 0), b3, voffB);
;             PG8_BAR; PG8_WAIT_L(0); PG8_MMA(0, 1, At, B1); PG8_BAR;
;             PG8_LDA(At, 1, 1); PG8_STAGE(PG8_SA(1, 0), a3, voffA);
;             PG8_BAR; PG8_WAIT_L(0); PG8_MMA(1, 0, At, B0); PG8_BAR; PG8_SCHED;
;             PG8_STAGE(PG8_SB(1, 1), b3 + hstep, voffB);
;             PG8_WAIT_V(6); PG8_BAR; PG8_MMA(1, 1, At, B1); PG8_BAR;
;             }
;         }
;         if constexpr (ALIGN_EPI) { if (wr == 0) PG8_BAR; }
	s_setprio 0
	s_add_i32 s26, s65, s93
	v_lshl_add_u64 v[162:163], v[162:163], 0, s[30:31]
	s_mov_b32 m0, s26
	ds_read_b128 v[178:181], v165 offset:49152
	ds_read_b128 v[182:185], v165 offset:50176
	ds_read_b128 v[186:189], v165 offset:51200
	ds_read_b128 v[198:201], v165 offset:52224
	ds_read_b128 v[202:205], v165 offset:53248
	ds_read_b128 v[206:209], v165 offset:54272
	ds_read_b128 v[210:213], v165 offset:55296
	ds_read_b128 v[220:223], v165 offset:56320
	global_load_lds_dwordx4 v[162:163], off
	s_add_i32 m0, s26, 0x2000
	s_add_u32 s26, s86, 0x40080
	v_lshl_add_u64 v[162:163], v[190:191], 0, s[30:31]
	s_addc_u32 s27, s87, 0
	s_add_i32 s65, s66, s93
	global_load_lds_dwordx4 v[162:163], off
	v_lshl_add_u64 v[162:163], s[26:27], 0, v[148:149]
	s_mov_b32 m0, s65
	s_nop 0
	global_load_lds_dwordx4 v[162:163], off
	v_lshl_add_u64 v[162:163], s[26:27], 0, v[144:145]
	s_add_i32 m0, s65, 0x2000
	s_nop 0
	global_load_lds_dwordx4 v[162:163], off
	v_lshl_add_u64 v[162:163], v[194:195], 0, s[30:31]
	s_mov_b32 m0, s4
	s_nop 0
	global_load_lds_dwordx4 v[162:163], off
	v_lshl_add_u64 v[162:163], v[196:197], 0, s[30:31]
	s_mov_b32 m0, s5
	s_nop 0
	global_load_lds_dwordx4 v[162:163], off
	s_waitcnt vmcnt(8)
	s_waitcnt lgkmcnt(0)
	s_barrier
	s_setprio 1
	s_waitcnt lgkmcnt(0)
	v_mfma_f32_16x16x32_bf16 v[60:63], v[128:131], v[178:181], v[60:63]
	v_mfma_f32_16x16x32_bf16 v[56:59], v[136:139], v[178:181], v[56:59]
	v_mfma_f32_16x16x32_bf16 v[44:47], v[128:131], v[186:189], v[44:47]
	v_mfma_f32_16x16x32_bf16 v[40:43], v[136:139], v[186:189], v[40:43]
	v_mfma_f32_16x16x32_bf16 v[28:31], v[128:131], v[202:205], v[28:31]
	v_mfma_f32_16x16x32_bf16 v[24:27], v[136:139], v[202:205], v[24:27]
	v_mfma_f32_16x16x32_bf16 v[12:15], v[128:131], v[210:213], v[12:15]
	v_mfma_f32_16x16x32_bf16 v[8:11], v[136:139], v[210:213], v[8:11]
	v_mfma_f32_16x16x32_bf16 v[60:63], v[132:135], v[182:185], v[60:63]
	v_mfma_f32_16x16x32_bf16 v[56:59], v[140:143], v[182:185], v[56:59]
	v_mfma_f32_16x16x32_bf16 v[44:47], v[132:135], v[198:201], v[44:47]
	v_mfma_f32_16x16x32_bf16 v[40:43], v[140:143], v[198:201], v[40:43]
	v_mfma_f32_16x16x32_bf16 v[28:31], v[132:135], v[206:209], v[28:31]
	v_mfma_f32_16x16x32_bf16 v[24:27], v[140:143], v[206:209], v[24:27]
	v_mfma_f32_16x16x32_bf16 v[12:15], v[132:135], v[220:223], v[12:15]
	v_mfma_f32_16x16x32_bf16 v[8:11], v[140:143], v[220:223], v[8:11]
	s_setprio 0
	s_setprio 1
	v_mfma_f32_16x16x32_bf16 v[52:55], v[158:161], v[178:181], v[52:55]
	v_mfma_f32_16x16x32_bf16 v[48:51], v[170:173], v[178:181], v[48:51]
	v_mfma_f32_16x16x32_bf16 v[36:39], v[158:161], v[186:189], v[36:39]
	v_mfma_f32_16x16x32_bf16 v[32:35], v[170:173], v[186:189], v[32:35]
	v_mfma_f32_16x16x32_bf16 v[20:23], v[158:161], v[202:205], v[20:23]
	v_mfma_f32_16x16x32_bf16 v[16:19], v[170:173], v[202:205], v[16:19]
	v_mfma_f32_16x16x32_bf16 v[4:7], v[158:161], v[210:213], v[4:7]
	v_mfma_f32_16x16x32_bf16 v[0:3], v[170:173], v[210:213], v[0:3]
	v_mfma_f32_16x16x32_bf16 v[52:55], v[166:169], v[182:185], v[52:55]
	v_mfma_f32_16x16x32_bf16 v[48:51], v[174:177], v[182:185], v[48:51]
	v_mfma_f32_16x16x32_bf16 v[36:39], v[166:169], v[198:201], v[36:39]
	v_mfma_f32_16x16x32_bf16 v[32:35], v[174:177], v[198:201], v[32:35]
	v_mfma_f32_16x16x32_bf16 v[20:23], v[166:169], v[206:209], v[20:23]
	v_mfma_f32_16x16x32_bf16 v[16:19], v[174:177], v[206:209], v[16:19]
	v_mfma_f32_16x16x32_bf16 v[4:7], v[166:169], v[220:223], v[4:7]
	v_mfma_f32_16x16x32_bf16 v[0:3], v[174:177], v[220:223], v[0:3]
	s_barrier
	s_setprio 0
	s_add_i32 s64, s64, 2
	s_add_u32 s10, s10, 0x100
	s_addc_u32 s11, s11, 0
	s_add_u32 s84, s84, 0x100
	s_addc_u32 s85, s85, 0
	s_cmp_gt_u32 s64, 13
	s_cbranch_scc0 .LBB0_143
	s_and_b64 vcc, exec, s[72:73]
	s_cbranch_vccz .LBB0_146
	s_barrier

; #define PG8_STAGE(bufoff, gbase, voff) do { _Pragma("unroll") for (int _i = 0; _i < 2; ++_i) \
;         __builtin_amdgcn_global_load_lds((const unsigned*)((const char*)(gbase) + (voff)[_i]), (PG8_LAS unsigned*)(lds + (bufoff) + ldsw + _i * 8192), 16, 0, 0); } while (0)
; #define PG8_LDA(dst, b, h) do { _Pragma("unroll") for (int m = 0; m < 4; ++m) _Pragma("unroll") for (int k = 0; k < 2; ++k) dst[m][k] = *(const PG8_LAS bf16x8*)(lds + PG8_SA(b, h) + aoff + m * 2048 + k * 1024); } while (0)
; #define PG8_LDB(dst, b, h) do { _Pragma("unroll") for (int n = 0; n < 2; ++n) _Pragma("unroll") for (int k = 0; k < 2; ++k) dst[n][k] = *(const PG8_LAS bf16x8*)(lds + PG8_SB(b, h) + boff + n * 2048 + k * 1024); } while (0)
; #define PG8_MMA(ai, bj, At, Bt) do { __builtin_amdgcn_s_setprio(1); _Pragma("unroll") for (int m = 0; m < 4; ++m) _Pragma("unroll") for (int n = 0; n < 2; ++n) _Pragma("unroll") for (int k = 0; k < 2; ++k) \
;         acc[ai][bj][m][n] = __builtin_amdgcn_mfma_f32_16x16x32_bf16(Bt[n][k], At[m][k], acc[ai][bj][m][n], 0, 0, 0); __builtin_amdgcn_s_setprio(0); } while (0)
; #define PG8_WAIT_V(n) asm volatile("s_waitcnt vmcnt(" #n ")" ::: "memory")
; #define PG8_BAR __builtin_amdgcn_s_barrier()
; template <class Epi, class Sched, bool ALIGN_EPI = false, bool SP2 = false>
; __device__ __forceinline__ void gemm_phase(PG8_LAS unsigned char* lds, const Gemm g, const Sched& S, const Epi& E, int wid0) {
;     ...
;         for (int t = 0; t < nt; t += 2) {
;             const bool last = (t == nt - 2);
;             const char* a1 = cA + (size_t)(t + 1) * kstep;
;             const char* a2 = last ? nA : cA + (size_t)(t + 2) * kstep; const char* b2 = last ? nB : cB + (size_t)(t + 2) * kstep;
;             const char* a3 = a2 + kstep; const char* b3 = b2 + kstep;
;             if (last && has_next) S.a_ready(nxt);
;             if constexpr (SP2) {
;             PG8_LDB(B0, 0, 0); PG8_LDB(B1, 0, 1); PG8_SCHED; PG8_LDA(At, 0, 0); PG8_STAGE(PG8_SA(1, 1), a1 + hstep, voffA);
;             PG8_WAIT_V(8); PG8_WAIT_L(0); PG8_BAR; PG8_MMA(0, 0, At, B0); PG8_MMA(0, 1, At, B1); PG8_BAR; PG8_SCHED;
;             PG8_LDA(At, 0, 1); PG8_STAGE(PG8_SB(0, 0), b2, voffB); PG8_STAGE(PG8_SB(0, 1), b2 + hstep, voffB); PG8_STAGE(PG8_SA(0, 0), a2, voffA);
;             PG8_WAIT_V(8); PG8_WAIT_L(0); PG8_BAR; PG8_MMA(1, 0, At, B0); PG8_MMA(1, 1, At, B1); PG8_BAR; PG8_SCHED;
.LBB0_167:
	s_add_u32 s26, s82, 0xfffc0080
	s_addc_u32 s27, s83, -1
	s_add_i32 s65, 0, 0x10000
	s_cmp_eq_u32 s64, 12
	s_cselect_b32 s87, s75, s27
	s_cselect_b32 s86, s94, s26
	s_cselect_b32 s85, s73, s11
	s_cselect_b32 s84, s95, s10
	s_add_i32 s66, 0, 0x14000
	v_add_u32_e32 v108, s65, v161
	v_add_u32_e32 v158, s66, v161
	ds_read_b128 v[96:99], v108
	ds_read_b128 v[100:103], v108 offset:1024
	ds_read_b128 v[104:107], v108 offset:2048
	ds_read_b128 v[108:111], v108 offset:3072
	ds_read_b128 v[154:157], v158
	ds_read_b128 v[164:167], v158 offset:1024
	ds_read_b128 v[168:171], v158 offset:2048
	ds_read_b128 v[172:175], v158 offset:3072
	v_lshl_add_u64 v[158:159], s[82:83], 0, v[152:153]
	s_add_i32 m0, s7, 0xc000
	ds_read_b128 v[176:179], v163
	ds_read_b128 v[180:183], v163 offset:1024
	ds_read_b128 v[184:187], v163 offset:2048
	ds_read_b128 v[188:191], v163 offset:3072
	ds_read_b128 v[198:201], v163 offset:4096
	ds_read_b128 v[202:205], v163 offset:5120
	ds_read_b128 v[206:209], v163 offset:6144
	ds_read_b128 v[210:213], v163 offset:7168
	global_load_lds_dwordx4 v[158:159], off
	v_lshl_add_u64 v[158:159], s[82:83], 0, v[150:151]
	s_add_i32 m0, s7, 0xe000
	s_nop 0
	global_load_lds_dwordx4 v[158:159], off
	s_waitcnt vmcnt(8)
	s_waitcnt lgkmcnt(0)
	s_barrier
	s_setprio 1
	s_waitcnt lgkmcnt(0)
	v_mfma_f32_16x16x32_bf16 v[140:143], v[96:99], v[176:179], v[140:143]
	v_mfma_f32_16x16x32_bf16 v[136:139], v[104:107], v[176:179], v[136:139]
	v_mfma_f32_16x16x32_bf16 v[124:127], v[96:99], v[184:187], v[124:127]
	v_mfma_f32_16x16x32_bf16 v[120:123], v[104:107], v[184:187], v[120:123]
	v_mfma_f32_16x16x32_bf16 v[92:95], v[96:99], v[198:201], v[92:95]
	v_mfma_f32_16x16x32_bf16 v[88:91], v[104:107], v[198:201], v[88:91]
	v_mfma_f32_16x16x32_bf16 v[76:79], v[96:99], v[206:209], v[76:79]
	v_mfma_f32_16x16x32_bf16 v[72:75], v[104:107], v[206:209], v[72:75]
	v_mfma_f32_16x16x32_bf16 v[140:143], v[100:103], v[180:183], v[140:143]
	v_mfma_f32_16x16x32_bf16 v[136:139], v[108:111], v[180:183], v[136:139]
	v_mfma_f32_16x16x32_bf16 v[124:127], v[100:103], v[188:191], v[124:127]
	v_mfma_f32_16x16x32_bf16 v[120:123], v[108:111], v[188:191], v[120:123]
	v_mfma_f32_16x16x32_bf16 v[92:95], v[100:103], v[202:205], v[92:95]
	v_mfma_f32_16x16x32_bf16 v[88:91], v[108:111], v[202:205], v[88:91]
	v_mfma_f32_16x16x32_bf16 v[76:79], v[100:103], v[210:213], v[76:79]
	v_mfma_f32_16x16x32_bf16 v[72:75], v[108:111], v[210:213], v[72:75]
	s_setprio 0
	s_setprio 1
	v_mfma_f32_16x16x32_bf16 v[132:135], v[154:157], v[176:179], v[132:135]
	v_mfma_f32_16x16x32_bf16 v[128:131], v[168:171], v[176:179], v[128:131]
	v_mfma_f32_16x16x32_bf16 v[116:119], v[154:157], v[184:187], v[116:119]
	v_mfma_f32_16x16x32_bf16 v[112:115], v[168:171], v[184:187], v[112:115]
	v_mfma_f32_16x16x32_bf16 v[84:87], v[154:157], v[198:201], v[84:87]
	v_mfma_f32_16x16x32_bf16 v[80:83], v[168:171], v[198:201], v[80:83]
	v_mfma_f32_16x16x32_bf16 v[68:71], v[154:157], v[206:209], v[68:71]
	v_mfma_f32_16x16x32_bf16 v[64:67], v[168:171], v[206:209], v[64:67]
	v_mfma_f32_16x16x32_bf16 v[132:135], v[164:167], v[180:183], v[132:135]
	v_mfma_f32_16x16x32_bf16 v[128:131], v[172:175], v[180:183], v[128:131]
	v_mfma_f32_16x16x32_bf16 v[116:119], v[164:167], v[188:191], v[116:119]
	v_mfma_f32_16x16x32_bf16 v[112:115], v[172:175], v[188:191], v[112:115]
	v_mfma_f32_16x16x32_bf16 v[84:87], v[164:167], v[202:205], v[84:87]
	v_mfma_f32_16x16x32_bf16 v[80:83], v[172:175], v[202:205], v[80:83]
	v_mfma_f32_16x16x32_bf16 v[68:71], v[164:167], v[210:213], v[68:71]
	v_mfma_f32_16x16x32_bf16 v[64:67], v[172:175], v[210:213], v[64:67]
	s_barrier
	s_setprio 0
	s_add_i32 s26, s65, s6
	v_lshl_add_u64 v[158:159], s[84:85], 0, v[192:193]
	s_mov_b32 m0, s26
	ds_read_b128 v[176:179], v163 offset:16384
	ds_read_b128 v[180:183], v163 offset:17408
	ds_read_b128 v[184:187], v163 offset:18432
	ds_read_b128 v[188:191], v163 offset:19456
	ds_read_b128 v[198:201], v163 offset:20480
	ds_read_b128 v[202:205], v163 offset:21504
	ds_read_b128 v[206:209], v163 offset:22528
	ds_read_b128 v[210:213], v163 offset:23552
	global_load_lds_dwordx4 v[158:159], off
	s_add_i32 m0, s26, 0x2000
	s_add_u32 s26, s84, 0x40000
	v_lshl_add_u64 v[194:195], s[84:85], 0, v[144:145]
	s_addc_u32 s27, s85, 0
	s_add_i32 s65, s66, s6
	global_load_lds_dwordx4 v[194:195], off
	v_lshl_add_u64 v[196:197], s[26:27], 0, v[192:193]
	s_mov_b32 m0, s65
	v_lshl_add_u64 v[214:215], s[86:87], 0, v[146:147]
	global_load_lds_dwordx4 v[196:197], off
	v_lshl_add_u64 v[196:197], s[26:27], 0, v[144:145]
	s_add_i32 m0, s65, 0x2000
	s_nop 0
	global_load_lds_dwordx4 v[196:197], off
	v_lshl_add_u64 v[196:197], s[86:87], 0, v[148:149]
	s_mov_b32 m0, s7
	s_nop 0
	global_load_lds_dwordx4 v[196:197], off
	s_mov_b32 m0, s44
	s_nop 0
	global_load_lds_dwordx4 v[214:215], off
	s_waitcnt vmcnt(8)
	s_waitcnt lgkmcnt(0)
	s_barrier
; #define PG8_STAGE(bufoff, gbase, voff) do { _Pragma("unroll") for (int _i = 0; _i < 2; ++_i) \
;         __builtin_amdgcn_global_load_lds((const unsigned*)((const char*)(gbase) + (voff)[_i]), (PG8_LAS unsigned*)(lds + (bufoff) + ldsw + _i * 8192), 16, 0, 0); } while (0)
; #define PG8_LDA(dst, b, h) do { _Pragma("unroll") for (int m = 0; m < 4; ++m) _Pragma("unroll") for (int k = 0; k < 2; ++k) dst[m][k] = *(const PG8_LAS bf16x8*)(lds + PG8_SA(b, h) + aoff + m * 2048 + k * 1024); } while (0)
; #define PG8_LDB(dst, b, h) do { _Pragma("unroll") for (int n = 0; n < 2; ++n) _Pragma("unroll") for (int k = 0; k < 2; ++k) dst[n][k] = *(const PG8_LAS bf16x8*)(lds + PG8_SB(b, h) + boff + n * 2048 + k * 1024); } while (0)
; #define PG8_MMA(ai, bj, At, Bt) do { __builtin_amdgcn_s_setprio(1); _Pragma("unroll") for (int m = 0; m < 4; ++m) _Pragma("unroll") for (int n = 0; n < 2; ++n) _Pragma("unroll") for (int k = 0; k < 2; ++k) \
;         acc[ai][bj][m][n] = __builtin_amdgcn_mfma_f32_16x16x32_bf16(Bt[n][k], At[m][k], acc[ai][bj][m][n], 0, 0, 0); __builtin_amdgcn_s_setprio(0); } while (0)
; #define PG8_WAIT_V(n) asm volatile("s_waitcnt vmcnt(" #n ")" ::: "memory")
; #define PG8_WAIT_L(n) asm volatile("s_waitcnt lgkmcnt(" #n ")" ::: "memory")
; #define PG8_BAR __builtin_amdgcn_s_barrier()
; #define PG8_SCHED __builtin_amdgcn_sched_barrier(0)
; template <class Epi, class Sched, bool ALIGN_EPI = false, bool SP2 = false>
; __device__ __forceinline__ void gemm_phase(PG8_LAS unsigned char* lds, const Gemm g, const Sched& S, const Epi& E, int wid0) {
;     ...
;             PG8_WAIT_V(8); PG8_WAIT_L(0); PG8_BAR; PG8_MMA(1, 0, At, B0); PG8_MMA(1, 1, At, B1); PG8_BAR; PG8_SCHED;
;             PG8_LDB(B0, 1, 0); PG8_LDB(B1, 1, 1); PG8_SCHED; PG8_LDA(At, 1, 0); PG8_STAGE(PG8_SA(0, 1), a2 + hstep, voffA);
;             PG8_WAIT_V(8); PG8_WAIT_L(0); PG8_BAR; PG8_MMA(0, 0, At, B0); PG8_MMA(0, 1, At, B1); PG8_BAR; PG8_SCHED;
	s_setprio 1
	s_waitcnt lgkmcnt(0)
	v_mfma_f32_16x16x32_bf16 v[60:63], v[96:99], v[176:179], v[60:63]
	v_mfma_f32_16x16x32_bf16 v[56:59], v[104:107], v[176:179], v[56:59]
	v_mfma_f32_16x16x32_bf16 v[48:51], v[96:99], v[184:187], v[48:51]
	v_mfma_f32_16x16x32_bf16 v[40:43], v[104:107], v[184:187], v[40:43]
	v_mfma_f32_16x16x32_bf16 v[32:35], v[96:99], v[198:201], v[32:35]
	v_mfma_f32_16x16x32_bf16 v[24:27], v[104:107], v[198:201], v[24:27]
	v_mfma_f32_16x16x32_bf16 v[16:19], v[96:99], v[206:209], v[16:19]
	v_mfma_f32_16x16x32_bf16 v[8:11], v[104:107], v[206:209], v[8:11]
	v_mfma_f32_16x16x32_bf16 v[60:63], v[100:103], v[180:183], v[60:63]
	v_mfma_f32_16x16x32_bf16 v[56:59], v[108:111], v[180:183], v[56:59]
	v_mfma_f32_16x16x32_bf16 v[48:51], v[100:103], v[188:191], v[48:51]
	v_mfma_f32_16x16x32_bf16 v[40:43], v[108:111], v[188:191], v[40:43]
	v_mfma_f32_16x16x32_bf16 v[32:35], v[100:103], v[202:205], v[32:35]
	v_mfma_f32_16x16x32_bf16 v[24:27], v[108:111], v[202:205], v[24:27]
	v_mfma_f32_16x16x32_bf16 v[16:19], v[100:103], v[210:213], v[16:19]
	v_mfma_f32_16x16x32_bf16 v[8:11], v[108:111], v[210:213], v[8:11]
	s_setprio 0
	s_setprio 1
	v_mfma_f32_16x16x32_bf16 v[52:55], v[154:157], v[176:179], v[52:55]
	v_mfma_f32_16x16x32_bf16 v[44:47], v[168:171], v[176:179], v[44:47]
	v_mfma_f32_16x16x32_bf16 v[36:39], v[154:157], v[184:187], v[36:39]
	v_mfma_f32_16x16x32_bf16 v[28:31], v[168:171], v[184:187], v[28:31]
	v_mfma_f32_16x16x32_bf16 v[20:23], v[154:157], v[198:201], v[20:23]
	v_mfma_f32_16x16x32_bf16 v[12:15], v[168:171], v[198:201], v[12:15]
	v_mfma_f32_16x16x32_bf16 v[4:7], v[154:157], v[206:209], v[4:7]
	v_mfma_f32_16x16x32_bf16 v[0:3], v[168:171], v[206:209], v[0:3]
	v_mfma_f32_16x16x32_bf16 v[52:55], v[164:167], v[180:183], v[52:55]
	v_mfma_f32_16x16x32_bf16 v[44:47], v[172:175], v[180:183], v[44:47]
	v_mfma_f32_16x16x32_bf16 v[36:39], v[164:167], v[188:191], v[36:39]
	v_mfma_f32_16x16x32_bf16 v[28:31], v[172:175], v[188:191], v[28:31]
	v_mfma_f32_16x16x32_bf16 v[20:23], v[164:167], v[202:205], v[20:23]
	v_mfma_f32_16x16x32_bf16 v[12:15], v[172:175], v[202:205], v[12:15]
	v_mfma_f32_16x16x32_bf16 v[4:7], v[164:167], v[210:213], v[4:7]
	v_mfma_f32_16x16x32_bf16 v[0:3], v[172:175], v[210:213], v[0:3]
	s_barrier
	s_setprio 0
	s_add_i32 s65, 0, 0x18000
	s_add_i32 s66, 0, 0x1c000
	v_add_u32_e32 v108, s65, v161
	v_add_u32_e32 v172, s66, v161
	ds_read_b128 v[96:99], v108
	ds_read_b128 v[100:103], v108 offset:1024
	ds_read_b128 v[104:107], v108 offset:2048
	ds_read_b128 v[108:111], v108 offset:3072
	ds_read_b128 v[154:157], v172
	ds_read_b128 v[164:167], v172 offset:1024
	ds_read_b128 v[168:171], v172 offset:2048
	ds_read_b128 v[172:175], v172 offset:3072
	s_add_u32 s26, s86, 0x40000
	s_addc_u32 s27, s87, 0
	s_mov_b32 m0, s45
	v_lshl_add_u64 v[220:221], s[26:27], 0, v[148:149]
	ds_read_b128 v[176:179], v163 offset:32768
	ds_read_b128 v[180:183], v163 offset:33792
	ds_read_b128 v[184:187], v163 offset:34816
	ds_read_b128 v[188:191], v163 offset:35840
	ds_read_b128 v[198:201], v163 offset:36864
	ds_read_b128 v[202:205], v163 offset:37888
	ds_read_b128 v[206:209], v163 offset:38912
	ds_read_b128 v[210:213], v163 offset:39936
	global_load_lds_dwordx4 v[220:221], off
	v_lshl_add_u64 v[220:221], s[26:27], 0, v[146:147]
	s_mov_b32 m0, s91
	s_nop 0
	global_load_lds_dwordx4 v[220:221], off
	s_waitcnt vmcnt(8)
	s_waitcnt lgkmcnt(0)
	s_barrier
	s_setprio 1
	s_waitcnt lgkmcnt(0)
	v_mfma_f32_16x16x32_bf16 v[140:143], v[96:99], v[176:179], v[140:143]
	v_mfma_f32_16x16x32_bf16 v[136:139], v[104:107], v[176:179], v[136:139]
	v_mfma_f32_16x16x32_bf16 v[124:127], v[96:99], v[184:187], v[124:127]
	v_mfma_f32_16x16x32_bf16 v[120:123], v[104:107], v[184:187], v[120:123]
	v_mfma_f32_16x16x32_bf16 v[92:95], v[96:99], v[198:201], v[92:95]
	v_mfma_f32_16x16x32_bf16 v[88:91], v[104:107], v[198:201], v[88:91]
	v_mfma_f32_16x16x32_bf16 v[76:79], v[96:99], v[206:209], v[76:79]
	v_mfma_f32_16x16x32_bf16 v[72:75], v[104:107], v[206:209], v[72:75]
	v_mfma_f32_16x16x32_bf16 v[140:143], v[100:103], v[180:183], v[140:143]
	v_mfma_f32_16x16x32_bf16 v[136:139], v[108:111], v[180:183], v[136:139]
	v_mfma_f32_16x16x32_bf16 v[124:127], v[100:103], v[188:191], v[124:127]
	v_mfma_f32_16x16x32_bf16 v[120:123], v[108:111], v[188:191], v[120:123]
	v_mfma_f32_16x16x32_bf16 v[92:95], v[100:103], v[202:205], v[92:95]
	v_mfma_f32_16x16x32_bf16 v[88:91], v[108:111], v[202:205], v[88:91]
	v_mfma_f32_16x16x32_bf16 v[76:79], v[100:103], v[210:213], v[76:79]
	v_mfma_f32_16x16x32_bf16 v[72:75], v[108:111], v[210:213], v[72:75]
	s_setprio 0
	s_setprio 1
	v_mfma_f32_16x16x32_bf16 v[132:135], v[154:157], v[176:179], v[132:135]
	v_mfma_f32_16x16x32_bf16 v[128:131], v[168:171], v[176:179], v[128:131]
	v_mfma_f32_16x16x32_bf16 v[116:119], v[154:157], v[184:187], v[116:119]
	v_mfma_f32_16x16x32_bf16 v[112:115], v[168:171], v[184:187], v[112:115]
	v_mfma_f32_16x16x32_bf16 v[84:87], v[154:157], v[198:201], v[84:87]
	v_mfma_f32_16x16x32_bf16 v[80:83], v[168:171], v[198:201], v[80:83]
	v_mfma_f32_16x16x32_bf16 v[68:71], v[154:157], v[206:209], v[68:71]
	v_mfma_f32_16x16x32_bf16 v[64:67], v[168:171], v[206:209], v[64:67]
	v_mfma_f32_16x16x32_bf16 v[132:135], v[164:167], v[180:183], v[132:135]
	v_mfma_f32_16x16x32_bf16 v[128:131], v[172:175], v[180:183], v[128:131]
	v_mfma_f32_16x16x32_bf16 v[116:119], v[164:167], v[188:191], v[116:119]
	v_mfma_f32_16x16x32_bf16 v[112:115], v[172:175], v[188:191], v[112:115]
	v_mfma_f32_16x16x32_bf16 v[84:87], v[164:167], v[202:205], v[84:87]
	v_mfma_f32_16x16x32_bf16 v[80:83], v[172:175], v[202:205], v[80:83]
	v_mfma_f32_16x16x32_bf16 v[68:71], v[164:167], v[210:213], v[68:71]
	v_mfma_f32_16x16x32_bf16 v[64:67], v[172:175], v[210:213], v[64:67]
	s_barrier
; #define PG8_STAGE(bufoff, gbase, voff) do { _Pragma("unroll") for (int _i = 0; _i < 2; ++_i) \
;         __builtin_amdgcn_global_load_lds((const unsigned*)((const char*)(gbase) + (voff)[_i]), (PG8_LAS unsigned*)(lds + (bufoff) + ldsw + _i * 8192), 16, 0, 0); } while (0)
; #define PG8_LDA(dst, b, h) do { _Pragma("unroll") for (int m = 0; m < 4; ++m) _Pragma("unroll") for (int k = 0; k < 2; ++k) dst[m][k] = *(const PG8_LAS bf16x8*)(lds + PG8_SA(b, h) + aoff + m * 2048 + k * 1024); } while (0)
; #define PG8_BAR __builtin_amdgcn_s_barrier()
; template <class Epi, class Sched, bool ALIGN_EPI = false, bool SP2 = false>
; __device__ __forceinline__ void gemm_phase(PG8_LAS unsigned char* lds, const Gemm g, const Sched& S, const Epi& E, int wid0) {
;     ...
;             PG8_LDA(At, 1, 1); PG8_STAGE(PG8_SB(1, 0), b3, voffB); PG8_STAGE(PG8_SB(1, 1), b3 + hstep, voffB); PG8_STAGE(PG8_SA(1, 0), a3, voffA);
;             PG8_WAIT_V(8); PG8_WAIT_L(0); PG8_BAR; PG8_MMA(1, 0, At, B0); PG8_MMA(1, 1, At, B1); PG8_BAR; PG8_SCHED;
;             } else {
;             PG8_LDB(B0, 0, 0); PG8_SCHED; PG8_LDA(At, 0, 0); PG8_STAGE(PG8_SA(1, 1), a1 + hstep, voffA);
;             PG8_WAIT_L(8); PG8_BAR; PG8_WAIT_L(0); PG8_MMA(0, 0, At, B0); PG8_BAR; PG8_SCHED;
;             PG8_LDB(B1, 0, 1); PG8_STAGE(PG8_SB(0, 0), b2, voffB);
;             PG8_BAR; PG8_WAIT_L(0); PG8_MMA(0, 1, At, B1); PG8_BAR;
;             PG8_LDA(At, 0, 1); PG8_STAGE(PG8_SA(0, 0), a2, voffA);
;             PG8_BAR; PG8_WAIT_L(0); PG8_MMA(1, 0, At, B0); PG8_BAR; PG8_SCHED;
;             PG8_STAGE(PG8_SB(0, 1), b2 + hstep, voffB);
;             PG8_WAIT_V(6); PG8_BAR; PG8_MMA(1, 1, At, B1); PG8_BAR;
;             PG8_LDB(B0, 1, 0); PG8_SCHED; PG8_LDA(At, 1, 0); PG8_STAGE(PG8_SA(0, 1), a2 + hstep, voffA);
;             PG8_WAIT_L(8); PG8_BAR; PG8_WAIT_L(0); PG8_MMA(0, 0, At, B0); PG8_BAR; PG8_SCHED;
;             PG8_LDB(B1, 1, 1); PG8_STAGE(PG8_SB(1, 0), b3, voffB);
;             PG8_BAR; PG8_WAIT_L(0); PG8_MMA(0, 1, At, B1); PG8_BAR;
;             PG8_LDA(At, 1, 1); PG8_STAGE(PG8_SA(1, 0), a3, voffA);
;             PG8_BAR; PG8_WAIT_L(0); PG8_MMA(1, 0, At, B0); PG8_BAR; PG8_SCHED;
;             PG8_STAGE(PG8_SB(1, 1), b3 + hstep, voffB);
;             PG8_WAIT_V(6); PG8_BAR; PG8_MMA(1, 1, At, B1); PG8_BAR;
;             }
;         }
;         if constexpr (ALIGN_EPI) { if (wr == 0) PG8_BAR; }
	s_setprio 0
	s_add_i32 s26, s65, s6
	v_lshl_add_u64 v[158:159], v[158:159], 0, s[30:31]
	s_mov_b32 m0, s26
	ds_read_b128 v[176:179], v163 offset:49152
	ds_read_b128 v[180:183], v163 offset:50176
	ds_read_b128 v[184:187], v163 offset:51200
	ds_read_b128 v[188:191], v163 offset:52224
	ds_read_b128 v[198:201], v163 offset:53248
	ds_read_b128 v[202:205], v163 offset:54272
	ds_read_b128 v[206:209], v163 offset:55296
	ds_read_b128 v[210:213], v163 offset:56320
	global_load_lds_dwordx4 v[158:159], off
	s_add_i32 m0, s26, 0x2000
	s_add_u32 s26, s84, 0x40080
	v_lshl_add_u64 v[158:159], v[194:195], 0, s[30:31]
	s_addc_u32 s27, s85, 0
	s_add_i32 s65, s66, s6
	global_load_lds_dwordx4 v[158:159], off
	v_lshl_add_u64 v[158:159], s[26:27], 0, v[192:193]
	s_mov_b32 m0, s65
	s_nop 0
	global_load_lds_dwordx4 v[158:159], off
	v_lshl_add_u64 v[158:159], s[26:27], 0, v[144:145]
	s_add_i32 m0, s65, 0x2000
	s_nop 0
	global_load_lds_dwordx4 v[158:159], off
	v_lshl_add_u64 v[158:159], v[196:197], 0, s[30:31]
	s_mov_b32 m0, s22
	s_nop 0
	global_load_lds_dwordx4 v[158:159], off
	v_lshl_add_u64 v[158:159], v[214:215], 0, s[30:31]
	s_mov_b32 m0, s92
	s_nop 0
	global_load_lds_dwordx4 v[158:159], off
	s_waitcnt vmcnt(8)
	s_waitcnt lgkmcnt(0)
	s_barrier
	s_setprio 1
	s_waitcnt lgkmcnt(0)
	v_mfma_f32_16x16x32_bf16 v[60:63], v[96:99], v[176:179], v[60:63]
	v_mfma_f32_16x16x32_bf16 v[56:59], v[104:107], v[176:179], v[56:59]
	v_mfma_f32_16x16x32_bf16 v[48:51], v[96:99], v[184:187], v[48:51]
	v_mfma_f32_16x16x32_bf16 v[40:43], v[104:107], v[184:187], v[40:43]
	v_mfma_f32_16x16x32_bf16 v[32:35], v[96:99], v[198:201], v[32:35]
	v_mfma_f32_16x16x32_bf16 v[24:27], v[104:107], v[198:201], v[24:27]
	v_mfma_f32_16x16x32_bf16 v[16:19], v[96:99], v[206:209], v[16:19]
	v_mfma_f32_16x16x32_bf16 v[8:11], v[104:107], v[206:209], v[8:11]
	v_mfma_f32_16x16x32_bf16 v[60:63], v[100:103], v[180:183], v[60:63]
	v_mfma_f32_16x16x32_bf16 v[56:59], v[108:111], v[180:183], v[56:59]
	v_mfma_f32_16x16x32_bf16 v[48:51], v[100:103], v[188:191], v[48:51]
	v_mfma_f32_16x16x32_bf16 v[40:43], v[108:111], v[188:191], v[40:43]
	v_mfma_f32_16x16x32_bf16 v[32:35], v[100:103], v[202:205], v[32:35]
	v_mfma_f32_16x16x32_bf16 v[24:27], v[108:111], v[202:205], v[24:27]
	v_mfma_f32_16x16x32_bf16 v[16:19], v[100:103], v[210:213], v[16:19]
	v_mfma_f32_16x16x32_bf16 v[8:11], v[108:111], v[210:213], v[8:11]
	s_setprio 0
	s_setprio 1
	v_mfma_f32_16x16x32_bf16 v[52:55], v[154:157], v[176:179], v[52:55]
	v_mfma_f32_16x16x32_bf16 v[44:47], v[168:171], v[176:179], v[44:47]
	v_mfma_f32_16x16x32_bf16 v[36:39], v[154:157], v[184:187], v[36:39]
	v_mfma_f32_16x16x32_bf16 v[28:31], v[168:171], v[184:187], v[28:31]
	v_mfma_f32_16x16x32_bf16 v[20:23], v[154:157], v[198:201], v[20:23]
	v_mfma_f32_16x16x32_bf16 v[12:15], v[168:171], v[198:201], v[12:15]
	v_mfma_f32_16x16x32_bf16 v[4:7], v[154:157], v[206:209], v[4:7]
	v_mfma_f32_16x16x32_bf16 v[0:3], v[168:171], v[206:209], v[0:3]
	v_mfma_f32_16x16x32_bf16 v[52:55], v[164:167], v[180:183], v[52:55]
	v_mfma_f32_16x16x32_bf16 v[44:47], v[172:175], v[180:183], v[44:47]
	v_mfma_f32_16x16x32_bf16 v[36:39], v[164:167], v[188:191], v[36:39]
	v_mfma_f32_16x16x32_bf16 v[28:31], v[172:175], v[188:191], v[28:31]
	v_mfma_f32_16x16x32_bf16 v[20:23], v[164:167], v[202:205], v[20:23]
	v_mfma_f32_16x16x32_bf16 v[12:15], v[172:175], v[202:205], v[12:15]
	v_mfma_f32_16x16x32_bf16 v[4:7], v[164:167], v[210:213], v[4:7]
	v_mfma_f32_16x16x32_bf16 v[0:3], v[172:175], v[210:213], v[0:3]
	s_barrier
	s_setprio 0
	s_add_i32 s64, s64, 2
	s_add_u32 s10, s10, 0x100
	s_addc_u32 s11, s11, 0
	s_add_u32 s82, s82, 0x100
	s_addc_u32 s83, s83, 0
	s_cmp_gt_u32 s64, 13
	s_cbranch_scc0 .LBB0_167
	s_and_b64 vcc, exec, s[70:71]
	s_cbranch_vccz .LBB0_170
	s_barrier

.LBB0_276:
	s_and_b64 vcc, exec, s[38:39]
	v_exp_f32_e32 v112, v112
	v_exp_f32_e32 v113, v113
	v_exp_f32_e32 v114, v114
	v_exp_f32_e32 v115, v115
	v_add_f32_e32 v80, v189, v112
	v_add_f32_e32 v81, v188, v113
	v_exp_f32_e32 v116, v116
	v_exp_f32_e32 v117, v117
	v_exp_f32_e32 v118, v118
	v_exp_f32_e32 v119, v119
	v_add_f32_e32 v80, v114, v80
	v_add_f32_e32 v81, v115, v81
	v_cvt_pk_bf16_f32 v188, v112, v113
	v_add_f32_e32 v80, v116, v80
	v_add_f32_e32 v81, v117, v81
	v_cvt_pk_bf16_f32 v189, v114, v115
	v_add_f32_e32 v100, v118, v80
	v_add_f32_e32 v101, v119, v81
	v_cvt_pk_bf16_f32 v190, v116, v117
	v_cvt_pk_bf16_f32 v191, v118, v119
	v_exp_f32_e32 v120, v120
	v_exp_f32_e32 v121, v121
	s_waitcnt lgkmcnt(6)
	v_mfma_f32_32x32x16_bf16 v[80:95], v[96:99], v[144:147], v[64:79]
	v_add_u32_e32 v96, v237, v226
	v_add_f32_e32 v194, v120, v100
	v_add_f32_e32 v195, v121, v101
	ds_read_b128 v[238:241], v96 offset:32768
	ds_read_b128 v[242:245], v96 offset:40960
	v_exp_f32_e32 v122, v122
	v_exp_f32_e32 v123, v123
	v_mfma_f32_32x32x16_bf16 v[96:111], v[184:187], v[144:147], v[64:79]
	v_add_u32_e32 v186, v237, v227
	v_add_f32_e32 v184, v122, v194
	v_add_f32_e32 v185, v123, v195
	ds_read_b128 v[246:249], v186 offset:32768
	ds_read_b128 v[250:253], v186 offset:40960
	s_waitcnt lgkmcnt(8)
	v_mfma_f32_32x32x16_bf16 v[80:95], v[180:183], v[148:151], v[80:95]
	v_exp_f32_e32 v124, v124
	v_exp_f32_e32 v125, v125
	v_add_f32_e32 v180, v124, v184
	v_add_f32_e32 v181, v125, v185
	s_cbranch_vccnz .Latt_dA0
	s_mov_b32 m0, s11
	s_nop 0
	global_load_lds_dwordx4 v206, s[98:99]
.Latt_dA0:
	v_mfma_f32_32x32x16_bf16 v[96:111], v[176:179], v[148:151], v[96:111]
	v_exp_f32_e32 v126, v126
	v_exp_f32_e32 v127, v127
	v_add_f32_e32 v237, v126, v180
	v_add_f32_e32 v219, v127, v181
	s_cbranch_vccnz .Latt_dA1
	s_add_i32 m0, s11, 0x4000
	s_nop 0
	global_load_lds_dwordx4 v202, s[100:101]
.Latt_dA1:
	s_waitcnt lgkmcnt(2)
	v_mfma_f32_32x32x16_bf16 v[80:95], v[238:241], v[152:155], v[80:95]
	v_add_u32_e32 v180, v236, v230
	ds_read_b128 v[238:241], v180 offset:16384
	ds_read_b128 v[194:197], v180 offset:20480
	v_cvt_pk_bf16_f32 v176, v120, v121
	v_cvt_pk_bf16_f32 v177, v122, v123
	v_mfma_f32_32x32x16_bf16 v[96:111], v[242:245], v[152:155], v[96:111]
	ds_read_b128 v[184:187], v180 offset:24576
	ds_read_b128 v[180:183], v180 offset:28672
	v_cvt_pk_bf16_f32 v178, v124, v125
	v_cvt_pk_bf16_f32 v179, v126, v127
	s_waitcnt lgkmcnt(4)
	v_mfma_f32_32x32x16_bf16 v[80:95], v[246:249], v[156:159], v[80:95]
	v_exp_f32_e32 v128, v128
	v_exp_f32_e32 v129, v129
	v_add_f32_e32 v237, v128, v237
	v_add_f32_e32 v219, v129, v219
	s_cbranch_vccnz .Latt_dA2
	s_add_i32 m0, s11, 0x2000
	s_nop 0
	global_load_lds_dwordx4 v204, s[98:99]
	s_add_u32 s98, s98, 0x10000
	s_addc_u32 s99, s99, 0
.Latt_dA2:
	v_mfma_f32_32x32x16_bf16 v[96:111], v[250:253], v[156:159], v[96:111]
	v_exp_f32_e32 v130, v130
	v_exp_f32_e32 v131, v131
	v_add_f32_e32 v237, v130, v237
	v_add_f32_e32 v219, v131, v219
	s_cbranch_vccnz .Latt_dA3
	s_add_i32 m0, s11, 0x6000
	s_nop 0
	global_load_lds_dwordx4 v200, s[100:101]
	s_add_u32 s100, s100, 0x80
	s_addc_u32 s101, s101, 0

.LBB0_281:
	s_andn2_b64 vcc, exec, s[38:39]
	v_exp_f32_e32 v80, v80
	v_exp_f32_e32 v81, v81
	v_exp_f32_e32 v82, v82
	v_exp_f32_e32 v83, v83
	v_add_f32_e32 v112, v189, v80
	v_add_f32_e32 v113, v188, v81
	v_exp_f32_e32 v84, v84
	v_exp_f32_e32 v85, v85
	v_exp_f32_e32 v86, v86
	v_exp_f32_e32 v87, v87
	v_add_f32_e32 v112, v82, v112
	v_add_f32_e32 v113, v83, v113
	v_cvt_pk_bf16_f32 v188, v80, v81
	v_add_f32_e32 v112, v84, v112
	v_add_f32_e32 v113, v85, v113
	v_cvt_pk_bf16_f32 v189, v82, v83
	v_add_f32_e32 v132, v86, v112
	v_add_f32_e32 v133, v87, v113
	v_cvt_pk_bf16_f32 v190, v84, v85
	v_cvt_pk_bf16_f32 v191, v86, v87
	v_exp_f32_e32 v88, v88
	v_exp_f32_e32 v89, v89
	s_waitcnt lgkmcnt(6)
	v_mfma_f32_32x32x16_bf16 v[112:127], v[128:131], v[144:147], v[64:79]
	v_add_u32_e32 v128, v209, v226
	v_add_f32_e32 v214, v88, v132
	v_add_f32_e32 v215, v89, v133
	ds_read_b128 v[194:197], v128
	ds_read_b128 v[210:213], v128 offset:8192
	v_exp_f32_e32 v90, v90
	v_exp_f32_e32 v91, v91
	v_mfma_f32_32x32x16_bf16 v[128:143], v[184:187], v[144:147], v[64:79]
	v_add_u32_e32 v186, v209, v227
	v_add_f32_e32 v184, v90, v214
	v_add_f32_e32 v185, v91, v215
	ds_read_b128 v[236:239], v186
	ds_read_b128 v[240:243], v186 offset:8192
	s_waitcnt lgkmcnt(8)
	v_mfma_f32_32x32x16_bf16 v[112:127], v[180:183], v[148:151], v[112:127]
	v_exp_f32_e32 v92, v92
	v_exp_f32_e32 v93, v93
	v_add_f32_e32 v180, v92, v184
	v_add_f32_e32 v181, v93, v185
	s_cbranch_vccnz .Latt_dB0
	s_mov_b32 m0, s10
	s_nop 0
	global_load_lds_dwordx4 v206, s[98:99]
.Latt_dB0:
	v_mfma_f32_32x32x16_bf16 v[128:143], v[176:179], v[148:151], v[128:143]
	v_exp_f32_e32 v94, v94
	v_exp_f32_e32 v95, v95
	v_add_f32_e32 v209, v94, v180
	v_add_f32_e32 v214, v95, v181
	s_cbranch_vccnz .Latt_dB1
	s_add_i32 m0, s10, 0x4000
	s_nop 0
	global_load_lds_dwordx4 v202, s[100:101]
.Latt_dB1:
	s_waitcnt lgkmcnt(2)
	v_mfma_f32_32x32x16_bf16 v[112:127], v[194:197], v[152:155], v[112:127]
	v_add_u32_e32 v180, v208, v230
	ds_read_b128 v[194:197], v180 offset:49152
	ds_read_b128 v[244:247], v180 offset:53248
	v_cvt_pk_bf16_f32 v176, v88, v89
	v_cvt_pk_bf16_f32 v177, v90, v91
	v_mfma_f32_32x32x16_bf16 v[128:143], v[210:213], v[152:155], v[128:143]
	ds_read_b128 v[184:187], v180 offset:57344
	ds_read_b128 v[180:183], v180 offset:61440
	v_cvt_pk_bf16_f32 v178, v92, v93
	v_cvt_pk_bf16_f32 v179, v94, v95
	s_waitcnt lgkmcnt(4)
	v_mfma_f32_32x32x16_bf16 v[112:127], v[236:239], v[156:159], v[112:127]
	v_exp_f32_e32 v96, v96
	v_exp_f32_e32 v97, v97
	v_add_f32_e32 v209, v96, v209
	v_add_f32_e32 v210, v97, v214
	s_cbranch_vccnz .Latt_dB2
	s_add_i32 m0, s10, 0x2000
	s_nop 0
	global_load_lds_dwordx4 v204, s[98:99]
	s_add_u32 s98, s98, 0x10000
	s_addc_u32 s99, s99, 0
.Latt_dB2:
	v_mfma_f32_32x32x16_bf16 v[128:143], v[240:243], v[156:159], v[128:143]
	v_exp_f32_e32 v98, v98
	v_exp_f32_e32 v99, v99
	v_add_f32_e32 v209, v98, v209
	v_add_f32_e32 v210, v99, v210
	s_cbranch_vccnz .Latt_dB3
	s_add_i32 m0, s10, 0x6000
	s_nop 0
	global_load_lds_dwordx4 v200, s[100:101]
	s_add_u32 s100, s100, 0x80
	s_addc_u32 s101, s101, 0

; __device__ __forceinline__ float shx(float v, int m, int lane) { return __builtin_bit_cast(float, __builtin_amdgcn_ds_bpermute((lane ^ m) << 2, __builtin_bit_cast(int, v))); }
; #define LAS __attribute__((address_space(3)))
; __device__ __forceinline__ void attn_unit2(LAS unsigned char* lds, const bf16_t* Q, const bf16_t* K, const bf16_t* VT, bf16_t* Y, const float* subg, float lam, float outscale, int b, int h, int qb, int wid0) {
;     ...
;     float lt = lsA + lsB; lt += shx(lt, 32, lane);
;     LAS float* xch = (LAS float*)(lds + 65536 + wq * 16384) + lane;
;     if (j == 1) { const float i1 = lam / lt;
; #pragma unroll
;         for (int r = 0; r < 16; ++r) { xch[(0 * 16 + r) * 64] = o0[r] * i1; xch[(1 * 16 + r) * 64] = o1[r] * i1; xch[(2 * 16 + r) * 64] = o2[r] * i1; xch[(3 * 16 + r) * 64] = o3[r] * i1; } }
;     __syncthreads();
;     if (j == 0) { const float i0 = 1.0f / lt; float ssq = 0.f;
; #pragma unroll
;         for (int r = 0; r < 16; ++r) { float c;
;             c = o0[r] * i0 - xch[(0 * 16 + r) * 64]; o0[r] = c; ssq += c * c; c = o1[r] * i0 - xch[(1 * 16 + r) * 64]; o1[r] = c; ssq += c * c;
;             c = o2[r] * i0 - xch[(2 * 16 + r) * 64]; o2[r] = c; ssq += c * c; c = o3[r] * i0 - xch[(3 * 16 + r) * 64]; o3[r] = c; ssq += c * c; }
.LBB0_285:
	s_cmpk_gt_u32 s90, 0xff
	s_waitcnt vmcnt(0) lgkmcnt(0)
	s_barrier
	s_cbranch_scc1 .LBB0_240
	v_div_scale_f32 v66, s[10:11], v65, v65, 1.0
	v_rcp_f32_e32 v67, v66
	v_div_scale_f32 v68, vcc, 1.0, v65, 1.0
	s_lshl_b32 s22, s89, 1
	v_fma_f32 v70, -v66, v67, 1.0
	v_fmac_f32_e32 v67, v70, v67
	v_mul_f32_e32 v70, v68, v67
	v_fma_f32 v71, -v66, v70, v68
	v_fmac_f32_e32 v70, v71, v67
	v_fma_f32 v66, -v66, v70, v68
	v_div_fmas_f32 v66, v66, v67, v70
	v_div_fixup_f32 v72, v66, v65, 1.0
	ds_read2st64_b32 v[76:77], v64 offset1:1
	ds_read2st64_b32 v[74:75], v64 offset0:2 offset1:3
	ds_read2st64_b32 v[78:79], v64 offset0:4 offset1:5
	ds_read2st64_b32 v[82:83], v64 offset0:6 offset1:7
	ds_read2st64_b32 v[88:89], v64 offset0:16 offset1:17
	ds_read2st64_b32 v[90:91], v64 offset0:18 offset1:19
	ds_read2st64_b32 v[92:93], v64 offset0:20 offset1:21
	ds_read2st64_b32 v[94:95], v64 offset0:22 offset1:23
	ds_read2st64_b32 v[96:97], v64 offset0:32 offset1:33
	ds_read2st64_b32 v[98:99], v64 offset0:34 offset1:35
	ds_read2st64_b32 v[100:101], v64 offset0:36 offset1:37
	ds_read2st64_b32 v[102:103], v64 offset0:38 offset1:39
	ds_read2st64_b32 v[84:85], v64 offset0:8 offset1:9
	ds_read2st64_b32 v[104:105], v64 offset0:10 offset1:11
	ds_read2st64_b32 v[106:107], v64 offset0:12 offset1:13
	ds_read2st64_b32 v[70:71], v64 offset0:14 offset1:15
	ds_read2st64_b32 v[108:109], v64 offset0:48 offset1:49
	ds_read2st64_b32 v[110:111], v64 offset0:50 offset1:51
	ds_read2st64_b32 v[112:113], v64 offset0:52 offset1:53
	ds_read2st64_b32 v[114:115], v64 offset0:54 offset1:55
	ds_read2st64_b32 v[116:117], v64 offset0:24 offset1:25
	ds_read2st64_b32 v[118:119], v64 offset0:26 offset1:27
	ds_read2st64_b32 v[120:121], v64 offset0:28 offset1:29
	ds_read2st64_b32 v[80:81], v64 offset0:30 offset1:31
	ds_read2st64_b32 v[122:123], v64 offset0:40 offset1:41
	ds_read2st64_b32 v[124:125], v64 offset0:42 offset1:43
	ds_read2st64_b32 v[126:127], v64 offset0:44 offset1:45
	ds_read2st64_b32 v[128:129], v64 offset0:46 offset1:47
	ds_read2st64_b32 v[130:131], v64 offset0:56 offset1:57
	ds_read2st64_b32 v[132:133], v64 offset0:58 offset1:59
	ds_read2st64_b32 v[134:135], v64 offset0:60 offset1:61
	ds_read2st64_b32 v[64:65], v64 offset0:62 offset1:63
	s_waitcnt lgkmcnt(8)
	v_fma_f32 v68, v46, v72, -v80
	v_mov_b32_e32 v46, v63
	v_mov_b32_e32 v80, v71
	v_pk_fma_f32 v[46:47], v[46:47], v[72:73], v[80:81] op_sel_hi:[1,0,1] neg_lo:[0,0,1] neg_hi:[0,0,1]
	v_pk_fma_f32 v[80:81], v[48:49], v[72:73], v[76:77] op_sel_hi:[1,0,1] neg_lo:[0,0,1] neg_hi:[0,0,1]
	v_pk_fma_f32 v[76:77], v[54:55], v[72:73], v[82:83] op_sel_hi:[1,0,1] neg_lo:[0,0,1] neg_hi:[0,0,1]
	v_pk_fma_f32 v[82:83], v[52:53], v[72:73], v[78:79] op_sel_hi:[1,0,1] neg_lo:[0,0,1] neg_hi:[0,0,1]
	v_pk_fma_f32 v[78:79], v[58:59], v[72:73], v[104:105] op_sel_hi:[1,0,1] neg_lo:[0,0,1] neg_hi:[0,0,1]
	v_pk_fma_f32 v[58:59], v[32:33], v[72:73], v[88:89] op_sel_hi:[1,0,1] neg_lo:[0,0,1] neg_hi:[0,0,1]
	v_mov_b32_e32 v67, v30
	s_waitcnt lgkmcnt(0)
	v_mov_b32_e32 v87, v64
	v_mov_b32_e32 v30, v15
	v_mov_b32_e32 v64, v129
	v_pk_mul_f32 v[140:141], v[80:81], v[80:81]
	v_pk_mul_f32 v[88:89], v[58:59], v[58:59]
	v_pk_fma_f32 v[48:49], v[42:43], v[72:73], v[118:119] op_sel_hi:[1,0,1] neg_lo:[0,0,1] neg_hi:[0,0,1]
	v_pk_fma_f32 v[42:43], v[0:1], v[72:73], v[96:97] op_sel_hi:[1,0,1] neg_lo:[0,0,1] neg_hi:[0,0,1]
	v_mov_b32_e32 v66, v14
	v_pk_fma_f32 v[14:15], v[30:31], v[72:73], v[64:65] op_sel_hi:[1,0,1] neg_lo:[0,0,1] neg_hi:[0,0,1]
	v_pk_mul_f32 v[96:97], v[42:43], v[42:43]
	v_pk_fma_f32 v[30:31], v[12:13], v[72:73], v[126:127] op_sel_hi:[1,0,1] neg_lo:[0,0,1] neg_hi:[0,0,1]
	v_pk_fma_f32 v[12:13], v[16:17], v[72:73], v[108:109] op_sel_hi:[1,0,1] neg_lo:[0,0,1] neg_hi:[0,0,1]
	v_add_f32_e32 v71, v140, v88
	v_pk_mul_f32 v[16:17], v[12:13], v[12:13]
	v_add_f32_e32 v71, v71, v96
	v_add_f32_e32 v16, v71, v16
	v_add_f32_e32 v16, v16, v141
	v_add_f32_e32 v16, v16, v89
	v_pk_fma_f32 v[74:75], v[50:51], v[72:73], v[74:75] op_sel_hi:[1,0,1] neg_lo:[0,0,1] neg_hi:[0,0,1]
	v_add_f32_e32 v16, v16, v97
	v_pk_mul_f32 v[138:139], v[74:75], v[74:75]
	v_pk_fma_f32 v[52:53], v[34:35], v[72:73], v[90:91] op_sel_hi:[1,0,1] neg_lo:[0,0,1] neg_hi:[0,0,1]
	v_add_f32_e32 v16, v16, v17
	v_pk_fma_f32 v[84:85], v[56:57], v[72:73], v[84:85] op_sel_hi:[1,0,1] neg_lo:[0,0,1] neg_hi:[0,0,1]
	v_pk_mul_f32 v[90:91], v[52:53], v[52:53]
	v_pk_fma_f32 v[56:57], v[36:37], v[72:73], v[92:93] op_sel_hi:[1,0,1] neg_lo:[0,0,1] neg_hi:[0,0,1]
	v_pk_fma_f32 v[36:37], v[2:3], v[72:73], v[98:99] op_sel_hi:[1,0,1] neg_lo:[0,0,1] neg_hi:[0,0,1]
	v_add_f32_e32 v16, v16, v138
	v_pk_mul_f32 v[98:99], v[36:37], v[36:37]
	v_pk_fma_f32 v[34:35], v[6:7], v[72:73], v[102:103] op_sel_hi:[1,0,1] neg_lo:[0,0,1] neg_hi:[0,0,1]
	v_pk_fma_f32 v[6:7], v[18:19], v[72:73], v[110:111] op_sel_hi:[1,0,1] neg_lo:[0,0,1] neg_hi:[0,0,1]
	v_add_f32_e32 v16, v16, v90
	v_pk_mul_f32 v[18:19], v[6:7], v[6:7]
	v_add_f32_e32 v16, v16, v98
	v_add_f32_e32 v16, v16, v18
	v_add_f32_e32 v16, v16, v139
	v_add_f32_e32 v16, v16, v91
	v_add_f32_e32 v16, v16, v99
	v_pk_mul_f32 v[144:145], v[82:83], v[82:83]
	v_add_f32_e32 v16, v16, v19
	v_pk_mul_f32 v[92:93], v[56:57], v[56:57]
	v_pk_fma_f32 v[54:55], v[40:41], v[72:73], v[116:117] op_sel_hi:[1,0,1] neg_lo:[0,0,1] neg_hi:[0,0,1]
	v_pk_fma_f32 v[40:41], v[4:5], v[72:73], v[100:101] op_sel_hi:[1,0,1] neg_lo:[0,0,1] neg_hi:[0,0,1]
	v_add_f32_e32 v16, v16, v144
	v_pk_mul_f32 v[100:101], v[40:41], v[40:41]
	v_pk_fma_f32 v[32:33], v[10:11], v[72:73], v[124:125] op_sel_hi:[1,0,1] neg_lo:[0,0,1] neg_hi:[0,0,1]
	v_pk_fma_f32 v[10:11], v[20:21], v[72:73], v[112:113] op_sel_hi:[1,0,1] neg_lo:[0,0,1] neg_hi:[0,0,1]
; __device__ __forceinline__ float shx(float v, int m, int lane) { return __builtin_bit_cast(float, __builtin_amdgcn_ds_bpermute((lane ^ m) << 2, __builtin_bit_cast(int, v))); }
; #define A2_ST(OX, eb) _Pragma("unroll") for (int rq = 0; rq < 4; ++rq) { const int e0 = 32 * (eb) + 8 * rq + 4 * hi; const f32x4 gq = *(const f32x4*)(subg + e0); \
;             u32x2 w; w.x = cvtpk_c(OX[4 * rq] * rs * gq[0], OX[4 * rq + 1] * rs * gq[1]); w.y = cvtpk_c(OX[4 * rq + 2] * rs * gq[2], OX[4 * rq + 3] * rs * gq[3]); *(u32x2*)(yp + e0) = w; }
; __device__ __forceinline__ void attn_unit2(LAS unsigned char* lds, const bf16_t* Q, const bf16_t* K, const bf16_t* VT, bf16_t* Y, const float* subg, float lam, float outscale, int b, int h, int qb, int wid0) {
;     ...
;     if (j == 0) { const float i0 = 1.0f / lt; float ssq = 0.f;
; #pragma unroll
;         for (int r = 0; r < 16; ++r) { float c;
;             c = o0[r] * i0 - xch[(0 * 16 + r) * 64]; o0[r] = c; ssq += c * c; c = o1[r] * i0 - xch[(1 * 16 + r) * 64]; o1[r] = c; ssq += c * c;
;             c = o2[r] * i0 - xch[(2 * 16 + r) * 64]; o2[r] = c; ssq += c * c; c = o3[r] * i0 - xch[(3 * 16 + r) * 64]; o3[r] = c; ssq += c * c; }
;         ssq += shx(ssq, 32, lane);
;         const float rs = outscale / sqrtf(ssq * (1.0f / 128.0f) + EPS);
;         bf16_t* yp = Y + (tok0 + q0 + i32) * 1024 + 512 + h * 128;
;     ...
;         A2_ST(o0, 0) A2_ST(o1, 1) A2_ST(o2, 2) A2_ST(o3, 3)
	v_add_f32_e32 v16, v16, v92
	v_pk_mul_f32 v[20:21], v[10:11], v[10:11]
	v_add_f32_e32 v16, v16, v100
	v_add_f32_e32 v16, v16, v20
	v_fma_f32 v70, v62, v72, -v70
	global_load_dwordx4 v[62:65], v192, s[70:71]
	global_load_dwordx4 v[148:151], v192, s[70:71] offset:32
	global_load_dwordx4 v[152:155], v192, s[70:71] offset:64
	global_load_dwordx4 v[156:159], v192, s[70:71] offset:96
	global_load_dwordx4 v[160:163], v192, s[70:71] offset:128
	global_load_dwordx4 v[164:167], v192, s[70:71] offset:160
	global_load_dwordx4 v[168:171], v192, s[70:71] offset:192
	global_load_dwordx4 v[172:175], v192, s[70:71] offset:224
	global_load_dwordx4 v[176:179], v192, s[70:71] offset:256
	global_load_dwordx4 v[180:183], v192, s[70:71] offset:288
	global_load_dwordx4 v[184:187], v192, s[70:71] offset:320
	global_load_dwordx4 v[188:191], v192, s[70:71] offset:352
	global_load_dwordx4 v[194:197], v192, s[70:71] offset:384
	global_load_dwordx4 v[236:239], v192, s[70:71] offset:416
	global_load_dwordx4 v[240:243], v192, s[70:71] offset:448
	global_load_dwordx4 v[244:247], v192, s[70:71] offset:480
	v_add_f32_e32 v16, v16, v145
	v_add_f32_e32 v16, v16, v93
	v_add_f32_e32 v16, v16, v101
	v_pk_mul_f32 v[142:143], v[76:77], v[76:77]
	v_pk_fma_f32 v[50:51], v[38:39], v[72:73], v[94:95] op_sel_hi:[1,0,1] neg_lo:[0,0,1] neg_hi:[0,0,1]
	v_add_f32_e32 v16, v16, v21
	v_pk_mul_f32 v[94:95], v[50:51], v[50:51]
	v_add_f32_e32 v16, v16, v142
	v_pk_mul_f32 v[102:103], v[34:35], v[34:35]
	v_pk_fma_f32 v[4:5], v[22:23], v[72:73], v[114:115] op_sel_hi:[1,0,1] neg_lo:[0,0,1] neg_hi:[0,0,1]
	v_add_f32_e32 v16, v16, v94
	v_pk_mul_f32 v[22:23], v[4:5], v[4:5]
	v_add_f32_e32 v16, v16, v102
	v_add_f32_e32 v16, v16, v22
	v_add_f32_e32 v16, v16, v143
	v_add_f32_e32 v16, v16, v95
	v_add_f32_e32 v16, v16, v103
	v_pk_mul_f32 v[146:147], v[84:85], v[84:85]
	v_add_f32_e32 v16, v16, v23
	v_pk_mul_f32 v[116:117], v[54:55], v[54:55]
	v_pk_fma_f32 v[38:39], v[8:9], v[72:73], v[122:123] op_sel_hi:[1,0,1] neg_lo:[0,0,1] neg_hi:[0,0,1]
	v_add_f32_e32 v16, v16, v146
	v_pk_mul_f32 v[122:123], v[38:39], v[38:39]
	v_pk_fma_f32 v[8:9], v[24:25], v[72:73], v[130:131] op_sel_hi:[1,0,1] neg_lo:[0,0,1] neg_hi:[0,0,1]
	v_add_f32_e32 v16, v16, v116
	v_pk_mul_f32 v[24:25], v[8:9], v[8:9]
	v_add_f32_e32 v16, v16, v122
	v_add_f32_e32 v16, v16, v24
	v_add_f32_e32 v16, v16, v147
	v_add_f32_e32 v16, v16, v117
	v_add_f32_e32 v16, v16, v123
	v_pk_mul_f32 v[104:105], v[78:79], v[78:79]
	v_add_f32_e32 v16, v16, v25
	v_pk_mul_f32 v[118:119], v[48:49], v[48:49]
	v_add_f32_e32 v16, v16, v104
	v_pk_mul_f32 v[124:125], v[32:33], v[32:33]
	v_pk_fma_f32 v[2:3], v[26:27], v[72:73], v[132:133] op_sel_hi:[1,0,1] neg_lo:[0,0,1] neg_hi:[0,0,1]
	v_add_f32_e32 v16, v16, v118
	v_pk_mul_f32 v[26:27], v[2:3], v[2:3]
	v_add_f32_e32 v16, v16, v124
	v_add_f32_e32 v16, v16, v26
	v_add_f32_e32 v16, v16, v105
	v_add_f32_e32 v16, v16, v119
	v_pk_fma_f32 v[60:61], v[60:61], v[72:73], v[106:107] op_sel_hi:[1,0,1] neg_lo:[0,0,1] neg_hi:[0,0,1]
	v_add_f32_e32 v16, v16, v125
	v_pk_mul_f32 v[106:107], v[60:61], v[60:61]
	v_pk_fma_f32 v[44:45], v[44:45], v[72:73], v[120:121] op_sel_hi:[1,0,1] neg_lo:[0,0,1] neg_hi:[0,0,1]
	v_add_f32_e32 v16, v16, v27
	v_pk_mul_f32 v[120:121], v[44:45], v[44:45]
	v_add_f32_e32 v16, v16, v106
	v_pk_mul_f32 v[126:127], v[30:31], v[30:31]
	v_pk_fma_f32 v[0:1], v[28:29], v[72:73], v[134:135] op_sel_hi:[1,0,1] neg_lo:[0,0,1] neg_hi:[0,0,1]
	v_add_f32_e32 v16, v16, v120
	v_pk_mul_f32 v[28:29], v[0:1], v[0:1]
	v_add_f32_e32 v16, v16, v126
	v_add_f32_e32 v16, v16, v28
	v_add_f32_e32 v16, v16, v107
	v_add_f32_e32 v16, v16, v121
	v_add_f32_e32 v16, v16, v127
	v_mov_b32_e32 v86, v128
	v_add_f32_e32 v16, v16, v29
	v_pk_fma_f32 v[66:67], v[66:67], v[72:73], v[86:87] op_sel_hi:[1,0,1] neg_lo:[0,0,1] neg_hi:[0,0,1]
	v_fmac_f32_e32 v16, v70, v70
	v_pk_mul_f32 v[86:87], v[66:67], v[66:67]
	v_fmac_f32_e32 v16, v68, v68
	v_add_f32_e32 v16, v16, v86
	v_pk_mul_f32 v[136:137], v[46:47], v[46:47]
	v_add_f32_e32 v16, v16, v87
	v_add_f32_e32 v16, v16, v136
	v_pk_mul_f32 v[128:129], v[14:15], v[14:15]
	v_add_f32_e32 v16, v16, v137
	v_add_f32_e32 v16, v16, v128
	v_add_f32_e32 v18, v16, v129
	ds_bpermute_b32 v19, v69, v18
	v_lshlrev_b64 v[16:17], 11, v[198:199]
	v_lshl_add_u64 v[16:17], s[0:1], 0, v[16:17]
	v_lshl_add_u64 v[16:17], v[16:17], 0, s[22:23]
	v_mov_b32_e32 v71, v46
	s_waitcnt lgkmcnt(0)
	v_add_f32_e32 v18, v18, v19
	v_fmamk_f32 v18, v18, 0x3c000000, v217
	v_mul_f32_e32 v19, 0x4f800000, v18
	v_cmp_gt_f32_e32 vcc, s59, v18
	v_mov_b32_e32 v69, v47
	s_nop 0
	v_cndmask_b32_e32 v18, v18, v19, vcc
	v_sqrt_f32_e32 v19, v18
	s_nop 0
	v_add_u32_e32 v20, -1, v19
	v_fma_f32 v21, -v20, v19, v18
	v_cmp_ge_f32_e64 s[38:39], 0, v21
	v_add_u32_e32 v21, 1, v19
	s_nop 0
	v_cndmask_b32_e64 v20, v19, v20, s[38:39]
	v_fma_f32 v19, -v21, v19, v18
	v_cmp_lt_f32_e64 s[38:39], 0, v19
	s_nop 1
	v_cndmask_b32_e64 v19, v20, v21, s[38:39]
	v_mul_f32_e32 v20, 0x37800000, v19
	v_cndmask_b32_e32 v19, v19, v20, vcc
	v_cmp_class_f32_e32 vcc, v18, v218
	s_nop 1
	v_cndmask_b32_e32 v22, v19, v18, vcc
	v_div_scale_f32 v23, s[10:11], v22, v22, v220
	v_rcp_f32_e32 v24, v23
	v_lshlrev_b32_e32 v18, 3, v221
	v_mov_b32_e32 v19, v193
	v_lshl_add_u64 v[20:21], v[16:17], 0, v[18:19]
	v_fma_f32 v16, -v23, v24, 1.0
	v_fmac_f32_e32 v24, v16, v24
	v_div_scale_f32 v16, vcc, v220, v22, v220
	v_mul_f32_e32 v17, v16, v24
	v_fma_f32 v18, -v23, v17, v16
	v_fmac_f32_e32 v17, v18, v24
	v_fma_f32 v16, -v23, v17, v16
	v_div_fmas_f32 v16, v16, v24, v17
	v_div_fixup_f32 v22, v16, v22, v220
	v_pk_mul_f32 v[16:17], v[80:81], v[22:23] op_sel_hi:[1,0]
	v_pk_mul_f32 v[18:19], v[74:75], v[22:23] op_sel_hi:[1,0]
	s_waitcnt vmcnt(0)
; #define A2_ST(OX, eb) _Pragma("unroll") for (int rq = 0; rq < 4; ++rq) { const int e0 = 32 * (eb) + 8 * rq + 4 * hi; const f32x4 gq = *(const f32x4*)(subg + e0); \
;             u32x2 w; w.x = cvtpk_c(OX[4 * rq] * rs * gq[0], OX[4 * rq + 1] * rs * gq[1]); w.y = cvtpk_c(OX[4 * rq + 2] * rs * gq[2], OX[4 * rq + 3] * rs * gq[3]); *(u32x2*)(yp + e0) = w; }
; __device__ __forceinline__ void attn_unit2(LAS unsigned char* lds, const bf16_t* Q, const bf16_t* K, const bf16_t* VT, bf16_t* Y, const float* subg, float lam, float outscale, int b, int h, int qb, int wid0) {
;     ...
;         const float rs = outscale / sqrtf(ssq * (1.0f / 128.0f) + EPS);
;         bf16_t* yp = Y + (tok0 + q0 + i32) * 1024 + 512 + h * 128;
;     ...
;         A2_ST(o0, 0) A2_ST(o1, 1) A2_ST(o2, 2) A2_ST(o3, 3)
	v_pk_mul_f32 v[16:17], v[62:63], v[16:17]
	v_pk_mul_f32 v[18:19], v[64:65], v[18:19]
	v_cvt_pk_bf16_f32 v16, v16, v17
	v_cvt_pk_bf16_f32 v17, v18, v19
	flat_store_dwordx2 v[20:21], v[16:17] offset:1024
	s_nop 0
	v_pk_mul_f32 v[24:25], v[82:83], v[22:23] op_sel_hi:[1,0]
	v_pk_mul_f32 v[26:27], v[78:79], v[22:23] op_sel_hi:[1,0]
	v_pk_mul_f32 v[12:13], v[12:13], v[22:23] op_sel_hi:[1,0]
	v_pk_mul_f32 v[6:7], v[6:7], v[22:23] op_sel_hi:[1,0]
	v_pk_mul_f32 v[4:5], v[4:5], v[22:23] op_sel_hi:[1,0]
	v_pk_mul_f32 v[8:9], v[8:9], v[22:23] op_sel_hi:[1,0]
	v_pk_mul_f32 v[2:3], v[2:3], v[22:23] op_sel_hi:[1,0]
	v_pk_mul_f32 v[0:1], v[0:1], v[22:23] op_sel_hi:[1,0]
	s_nop 0
	v_pk_mul_f32 v[16:17], v[148:149], v[24:25]
	v_pk_mul_f32 v[24:25], v[76:77], v[22:23] op_sel_hi:[1,0]
	v_cvt_pk_bf16_f32 v16, v16, v17
	v_pk_mul_f32 v[18:19], v[150:151], v[24:25]
	v_pk_mul_f32 v[24:25], v[84:85], v[22:23] op_sel_hi:[1,0]
	v_cvt_pk_bf16_f32 v17, v18, v19
	flat_store_dwordx2 v[20:21], v[16:17] offset:1040
	s_nop 0
	s_nop 0
	v_pk_mul_f32 v[16:17], v[152:153], v[24:25]
	v_pk_mul_f32 v[18:19], v[154:155], v[26:27]
	v_cvt_pk_bf16_f32 v16, v16, v17
	v_cvt_pk_bf16_f32 v17, v18, v19
	flat_store_dwordx2 v[20:21], v[16:17] offset:1056
	s_nop 0
	v_pk_mul_f32 v[24:25], v[60:61], v[22:23] op_sel_hi:[1,0]
	v_pk_mul_f32 v[26:27], v[70:71], v[22:23] op_sel_hi:[1,0]
	s_nop 0
	v_pk_mul_f32 v[16:17], v[24:25], v[156:157]
	v_pk_mul_f32 v[18:19], v[26:27], v[158:159]
	v_cvt_pk_bf16_f32 v16, v16, v17
	v_cvt_pk_bf16_f32 v17, v18, v19
	flat_store_dwordx2 v[20:21], v[16:17] offset:1072
	s_nop 0
	v_pk_mul_f32 v[24:25], v[58:59], v[22:23] op_sel_hi:[1,0]
	v_pk_mul_f32 v[26:27], v[52:53], v[22:23] op_sel_hi:[1,0]
	s_nop 0
	v_pk_mul_f32 v[16:17], v[24:25], v[160:161]
	v_pk_mul_f32 v[18:19], v[26:27], v[162:163]
	v_cvt_pk_bf16_f32 v16, v16, v17
	v_cvt_pk_bf16_f32 v17, v18, v19
	flat_store_dwordx2 v[20:21], v[16:17] offset:1088
	s_nop 0
	v_pk_mul_f32 v[24:25], v[56:57], v[22:23] op_sel_hi:[1,0]
	v_pk_mul_f32 v[26:27], v[50:51], v[22:23] op_sel_hi:[1,0]
	s_nop 0
	v_pk_mul_f32 v[16:17], v[24:25], v[164:165]
	v_pk_mul_f32 v[18:19], v[26:27], v[166:167]
	v_cvt_pk_bf16_f32 v16, v16, v17
	v_cvt_pk_bf16_f32 v17, v18, v19
	flat_store_dwordx2 v[20:21], v[16:17] offset:1104
	s_nop 0
	v_pk_mul_f32 v[24:25], v[54:55], v[22:23] op_sel_hi:[1,0]
	v_pk_mul_f32 v[26:27], v[48:49], v[22:23] op_sel_hi:[1,0]
	s_nop 0
	v_pk_mul_f32 v[16:17], v[24:25], v[168:169]
	v_pk_mul_f32 v[18:19], v[26:27], v[170:171]
	v_cvt_pk_bf16_f32 v16, v16, v17
	v_cvt_pk_bf16_f32 v17, v18, v19
	flat_store_dwordx2 v[20:21], v[16:17] offset:1120
	s_nop 0
	v_pk_mul_f32 v[24:25], v[44:45], v[22:23] op_sel_hi:[1,0]
	v_pk_mul_f32 v[26:27], v[68:69], v[22:23] op_sel_hi:[1,0]
	s_nop 0
	v_pk_mul_f32 v[16:17], v[24:25], v[172:173]
	v_pk_mul_f32 v[18:19], v[26:27], v[174:175]
	v_cvt_pk_bf16_f32 v16, v16, v17
	v_cvt_pk_bf16_f32 v17, v18, v19
	flat_store_dwordx2 v[20:21], v[16:17] offset:1136
	s_nop 0
	v_pk_mul_f32 v[24:25], v[42:43], v[22:23] op_sel_hi:[1,0]
	v_pk_mul_f32 v[26:27], v[36:37], v[22:23] op_sel_hi:[1,0]
	s_nop 0
	v_pk_mul_f32 v[16:17], v[24:25], v[176:177]
	v_pk_mul_f32 v[18:19], v[26:27], v[178:179]
	v_cvt_pk_bf16_f32 v16, v16, v17
	v_cvt_pk_bf16_f32 v17, v18, v19
	flat_store_dwordx2 v[20:21], v[16:17] offset:1152
	s_nop 0
	v_pk_mul_f32 v[24:25], v[40:41], v[22:23] op_sel_hi:[1,0]
	v_pk_mul_f32 v[26:27], v[34:35], v[22:23] op_sel_hi:[1,0]
	s_nop 0
	v_pk_mul_f32 v[16:17], v[24:25], v[180:181]
	v_pk_mul_f32 v[18:19], v[26:27], v[182:183]
	v_cvt_pk_bf16_f32 v16, v16, v17
	v_cvt_pk_bf16_f32 v17, v18, v19
	flat_store_dwordx2 v[20:21], v[16:17] offset:1168
	s_nop 0
	v_pk_mul_f32 v[24:25], v[38:39], v[22:23] op_sel_hi:[1,0]
	v_pk_mul_f32 v[26:27], v[32:33], v[22:23] op_sel_hi:[1,0]
	s_nop 0
	v_pk_mul_f32 v[16:17], v[24:25], v[184:185]
	v_pk_mul_f32 v[18:19], v[26:27], v[186:187]
	v_cvt_pk_bf16_f32 v16, v16, v17
	v_cvt_pk_bf16_f32 v17, v18, v19
	flat_store_dwordx2 v[20:21], v[16:17] offset:1184
	s_nop 0
	v_mov_b32_e32 v24, v66
	v_mov_b32_e32 v25, v14
	v_pk_mul_f32 v[26:27], v[30:31], v[22:23] op_sel_hi:[1,0]
	v_pk_mul_f32 v[24:25], v[24:25], v[22:23] op_sel_hi:[1,0]
	v_mov_b32_e32 v14, v67
	s_nop 0
	v_pk_mul_f32 v[16:17], v[26:27], v[188:189]
	v_pk_mul_f32 v[18:19], v[24:25], v[190:191]
	v_cvt_pk_bf16_f32 v16, v16, v17
	v_cvt_pk_bf16_f32 v17, v18, v19
	flat_store_dwordx2 v[20:21], v[16:17] offset:1200
	s_nop 0
	s_nop 0
	v_pk_mul_f32 v[12:13], v[12:13], v[194:195]
	v_pk_mul_f32 v[6:7], v[6:7], v[196:197]
	v_cvt_pk_bf16_f32 v12, v12, v13
	v_cvt_pk_bf16_f32 v13, v6, v7
	flat_store_dwordx2 v[20:21], v[12:13] offset:1216
	s_nop 0
	v_pk_mul_f32 v[6:7], v[10:11], v[22:23] op_sel_hi:[1,0]
	s_nop 0
	v_pk_mul_f32 v[4:5], v[4:5], v[238:239]
	v_pk_mul_f32 v[6:7], v[6:7], v[236:237]
	s_nop 0
	v_cvt_pk_bf16_f32 v6, v6, v7
	v_cvt_pk_bf16_f32 v7, v4, v5
	flat_store_dwordx2 v[20:21], v[6:7] offset:1232
	s_nop 0
	s_nop 0
	v_pk_mul_f32 v[4:5], v[8:9], v[240:241]
	v_pk_mul_f32 v[2:3], v[2:3], v[242:243]
	v_cvt_pk_bf16_f32 v4, v4, v5
	v_cvt_pk_bf16_f32 v5, v2, v3
	flat_store_dwordx2 v[20:21], v[4:5] offset:1248
	s_nop 0
	v_pk_mul_f32 v[6:7], v[14:15], v[22:23] op_sel_hi:[1,0]
	s_nop 0
	v_pk_mul_f32 v[0:1], v[0:1], v[244:245]
	v_pk_mul_f32 v[2:3], v[6:7], v[246:247]
	v_cvt_pk_bf16_f32 v0, v0, v1
	v_cvt_pk_bf16_f32 v1, v2, v3
	flat_store_dwordx2 v[20:21], v[0:1] offset:1264
	s_branch .LBB0_240

; __global__ void __launch_bounds__(512, 2) mk_fwd(Args args) {
;     ...
;                 for (int p = vcu; p < 256; p += G) {
;                     const int xcd = p >> 5, c = p & 31;
;     ...
; #pragma unroll 1
;                     for (int i = 0; i < 4; ++i) { const int bh = 2 * xcd + (i >> 1), qb = (i & 1) ? c : 63 - c;
;                         attn_unit2(lds, Qb, Kb, VT, Y, args.in[11] + l * 128, lam, 1.0f - lam0, bh >> 2, bh & 3, qb, wid); }
.LBB0_288:
	s_branch .LBB0_248
	s_nop 0

; #define PG8_STAGE(bufoff, gbase, voff) do { _Pragma("unroll") for (int _i = 0; _i < 2; ++_i) \
;         __builtin_amdgcn_global_load_lds((const unsigned*)((const char*)(gbase) + (voff)[_i]), (PG8_LAS unsigned*)(lds + (bufoff) + ldsw + _i * 8192), 16, 0, 0); } while (0)
; #define PG8_LDA(dst, b, h) do { _Pragma("unroll") for (int m = 0; m < 4; ++m) _Pragma("unroll") for (int k = 0; k < 2; ++k) dst[m][k] = *(const PG8_LAS bf16x8*)(lds + PG8_SA(b, h) + aoff + m * 2048 + k * 1024); } while (0)
; #define PG8_LDB(dst, b, h) do { _Pragma("unroll") for (int n = 0; n < 2; ++n) _Pragma("unroll") for (int k = 0; k < 2; ++k) dst[n][k] = *(const PG8_LAS bf16x8*)(lds + PG8_SB(b, h) + boff + n * 2048 + k * 1024); } while (0)
; #define PG8_MMA(ai, bj, At, Bt) do { __builtin_amdgcn_s_setprio(1); _Pragma("unroll") for (int m = 0; m < 4; ++m) _Pragma("unroll") for (int n = 0; n < 2; ++n) _Pragma("unroll") for (int k = 0; k < 2; ++k) \
;         acc[ai][bj][m][n] = __builtin_amdgcn_mfma_f32_16x16x32_bf16(Bt[n][k], At[m][k], acc[ai][bj][m][n], 0, 0, 0); __builtin_amdgcn_s_setprio(0); } while (0)
; #define PG8_WAIT_V(n) asm volatile("s_waitcnt vmcnt(" #n ")" ::: "memory")
; #define PG8_BAR __builtin_amdgcn_s_barrier()
; template <class Epi, class Sched, bool ALIGN_EPI = false, bool SP2 = false>
; __device__ __forceinline__ void gemm_phase(PG8_LAS unsigned char* lds, const Gemm g, const Sched& S, const Epi& E, int wid0) {
;     ...
;         for (int t = 0; t < nt; t += 2) {
;             const bool last = (t == nt - 2);
;             const char* a1 = cA + (size_t)(t + 1) * kstep;
;             const char* a2 = last ? nA : cA + (size_t)(t + 2) * kstep; const char* b2 = last ? nB : cB + (size_t)(t + 2) * kstep;
;             const char* a3 = a2 + kstep; const char* b3 = b2 + kstep;
;             if (last && has_next) S.a_ready(nxt);
;             if constexpr (SP2) {
;             PG8_LDB(B0, 0, 0); PG8_LDB(B1, 0, 1); PG8_SCHED; PG8_LDA(At, 0, 0); PG8_STAGE(PG8_SA(1, 1), a1 + hstep, voffA);
;             PG8_WAIT_V(8); PG8_WAIT_L(0); PG8_BAR; PG8_MMA(0, 0, At, B0); PG8_MMA(0, 1, At, B1); PG8_BAR; PG8_SCHED;
;             PG8_LDA(At, 0, 1); PG8_STAGE(PG8_SB(0, 0), b2, voffB); PG8_STAGE(PG8_SB(0, 1), b2 + hstep, voffB); PG8_STAGE(PG8_SA(0, 0), a2, voffA);
;             PG8_WAIT_V(8); PG8_WAIT_L(0); PG8_BAR; PG8_MMA(1, 0, At, B0); PG8_MMA(1, 1, At, B1); PG8_BAR; PG8_SCHED;
.LBB0_377:
	s_add_u32 s26, s84, 0xfffc0080
	s_addc_u32 s27, s85, -1
	s_add_i32 s65, 0, 0x10000
	s_cmp_eq_u32 s64, 12
	s_cselect_b32 vcc_hi, s22, s27
	s_cselect_b32 vcc_lo, s75, s26
	s_cselect_b32 s77, s73, s11
	s_cselect_b32 s76, s81, s10
	s_add_i32 s66, 0, 0x14000
	v_add_u32_e32 v156, s65, v143
	v_add_u32_e32 v172, s66, v143
	ds_read_b128 v[138:141], v156
	ds_read_b128 v[148:151], v156 offset:1024
	ds_read_b128 v[152:155], v156 offset:2048
	ds_read_b128 v[156:159], v156 offset:3072
	ds_read_b128 v[160:163], v172
	ds_read_b128 v[164:167], v172 offset:1024
	ds_read_b128 v[168:171], v172 offset:2048
	ds_read_b128 v[172:175], v172 offset:3072
	v_lshl_add_u64 v[210:211], s[84:85], 0, v[136:137]
	s_add_i32 m0, s83, 0xc000
	ds_read_b128 v[176:179], v147
	ds_read_b128 v[180:183], v147 offset:1024
	ds_read_b128 v[184:187], v147 offset:2048
	ds_read_b128 v[188:191], v147 offset:3072
	ds_read_b128 v[194:197], v147 offset:4096
	ds_read_b128 v[198:201], v147 offset:5120
	ds_read_b128 v[202:205], v147 offset:6144
	ds_read_b128 v[206:209], v147 offset:7168
	global_load_lds_dwordx4 v[210:211], off
	v_lshl_add_u64 v[210:211], s[84:85], 0, v[134:135]
	s_add_i32 m0, s83, 0xe000
	s_nop 0
	global_load_lds_dwordx4 v[210:211], off
	s_waitcnt vmcnt(8)
	s_waitcnt lgkmcnt(0)
	s_barrier
	s_setprio 1
	s_waitcnt lgkmcnt(0)
	v_mfma_f32_16x16x32_bf16 v[124:127], v[138:141], v[176:179], v[124:127]
	v_mfma_f32_16x16x32_bf16 v[120:123], v[152:155], v[176:179], v[120:123]
	v_mfma_f32_16x16x32_bf16 v[108:111], v[138:141], v[184:187], v[108:111]
	v_mfma_f32_16x16x32_bf16 v[104:107], v[152:155], v[184:187], v[104:107]
	v_mfma_f32_16x16x32_bf16 v[92:95], v[138:141], v[194:197], v[92:95]
	v_mfma_f32_16x16x32_bf16 v[88:91], v[152:155], v[194:197], v[88:91]
	v_mfma_f32_16x16x32_bf16 v[76:79], v[138:141], v[202:205], v[76:79]
	v_mfma_f32_16x16x32_bf16 v[72:75], v[152:155], v[202:205], v[72:75]
	v_mfma_f32_16x16x32_bf16 v[124:127], v[148:151], v[180:183], v[124:127]
	v_mfma_f32_16x16x32_bf16 v[120:123], v[156:159], v[180:183], v[120:123]
	v_mfma_f32_16x16x32_bf16 v[108:111], v[148:151], v[188:191], v[108:111]
	v_mfma_f32_16x16x32_bf16 v[104:107], v[156:159], v[188:191], v[104:107]
	v_mfma_f32_16x16x32_bf16 v[92:95], v[148:151], v[198:201], v[92:95]
	v_mfma_f32_16x16x32_bf16 v[88:91], v[156:159], v[198:201], v[88:91]
	v_mfma_f32_16x16x32_bf16 v[76:79], v[148:151], v[206:209], v[76:79]
	v_mfma_f32_16x16x32_bf16 v[72:75], v[156:159], v[206:209], v[72:75]
	s_setprio 0
	s_setprio 1
	v_mfma_f32_16x16x32_bf16 v[116:119], v[160:163], v[176:179], v[116:119]
	v_mfma_f32_16x16x32_bf16 v[112:115], v[168:171], v[176:179], v[112:115]
	v_mfma_f32_16x16x32_bf16 v[100:103], v[160:163], v[184:187], v[100:103]
	v_mfma_f32_16x16x32_bf16 v[96:99], v[168:171], v[184:187], v[96:99]
	v_mfma_f32_16x16x32_bf16 v[84:87], v[160:163], v[194:197], v[84:87]
	v_mfma_f32_16x16x32_bf16 v[80:83], v[168:171], v[194:197], v[80:83]
	v_mfma_f32_16x16x32_bf16 v[68:71], v[160:163], v[202:205], v[68:71]
	v_mfma_f32_16x16x32_bf16 v[64:67], v[168:171], v[202:205], v[64:67]
	v_mfma_f32_16x16x32_bf16 v[116:119], v[164:167], v[180:183], v[116:119]
	v_mfma_f32_16x16x32_bf16 v[112:115], v[172:175], v[180:183], v[112:115]
	v_mfma_f32_16x16x32_bf16 v[100:103], v[164:167], v[188:191], v[100:103]
	v_mfma_f32_16x16x32_bf16 v[96:99], v[172:175], v[188:191], v[96:99]
	v_mfma_f32_16x16x32_bf16 v[84:87], v[164:167], v[198:201], v[84:87]
	v_mfma_f32_16x16x32_bf16 v[80:83], v[172:175], v[198:201], v[80:83]
	v_mfma_f32_16x16x32_bf16 v[68:71], v[164:167], v[206:209], v[68:71]
	v_mfma_f32_16x16x32_bf16 v[64:67], v[172:175], v[206:209], v[64:67]
	s_barrier
	s_setprio 0
	s_add_i32 s26, s65, s69
	v_lshl_add_u64 v[210:211], s[76:77], 0, v[192:193]
	s_mov_b32 m0, s26
	ds_read_b128 v[176:179], v147 offset:16384
	ds_read_b128 v[180:183], v147 offset:17408
	ds_read_b128 v[184:187], v147 offset:18432
	ds_read_b128 v[188:191], v147 offset:19456
	ds_read_b128 v[194:197], v147 offset:20480
	ds_read_b128 v[198:201], v147 offset:21504
	ds_read_b128 v[202:205], v147 offset:22528
	ds_read_b128 v[206:209], v147 offset:23552
	global_load_lds_dwordx4 v[210:211], off
	s_add_i32 m0, s26, 0x2000
	s_add_u32 s26, s76, 0x40000
	v_lshl_add_u64 v[212:213], s[76:77], 0, v[132:133]
	s_addc_u32 s27, s77, 0
	s_add_i32 s65, s66, s69
	global_load_lds_dwordx4 v[212:213], off
	v_lshl_add_u64 v[214:215], s[26:27], 0, v[192:193]
	s_mov_b32 m0, s65
	v_lshl_add_u64 v[220:221], vcc, 0, v[130:131]
	global_load_lds_dwordx4 v[214:215], off
	v_lshl_add_u64 v[214:215], s[26:27], 0, v[132:133]
	s_add_i32 m0, s65, 0x2000
	s_nop 0
	global_load_lds_dwordx4 v[214:215], off
	v_lshl_add_u64 v[214:215], vcc, 0, v[128:129]
	s_mov_b32 m0, s83
	s_nop 0
	global_load_lds_dwordx4 v[214:215], off
	s_mov_b32 m0, s88
	s_nop 0
	global_load_lds_dwordx4 v[220:221], off
	s_waitcnt vmcnt(8)
	s_waitcnt lgkmcnt(0)
	s_barrier
; #define PG8_STAGE(bufoff, gbase, voff) do { _Pragma("unroll") for (int _i = 0; _i < 2; ++_i) \
;         __builtin_amdgcn_global_load_lds((const unsigned*)((const char*)(gbase) + (voff)[_i]), (PG8_LAS unsigned*)(lds + (bufoff) + ldsw + _i * 8192), 16, 0, 0); } while (0)
; #define PG8_LDA(dst, b, h) do { _Pragma("unroll") for (int m = 0; m < 4; ++m) _Pragma("unroll") for (int k = 0; k < 2; ++k) dst[m][k] = *(const PG8_LAS bf16x8*)(lds + PG8_SA(b, h) + aoff + m * 2048 + k * 1024); } while (0)
; #define PG8_LDB(dst, b, h) do { _Pragma("unroll") for (int n = 0; n < 2; ++n) _Pragma("unroll") for (int k = 0; k < 2; ++k) dst[n][k] = *(const PG8_LAS bf16x8*)(lds + PG8_SB(b, h) + boff + n * 2048 + k * 1024); } while (0)
; #define PG8_MMA(ai, bj, At, Bt) do { __builtin_amdgcn_s_setprio(1); _Pragma("unroll") for (int m = 0; m < 4; ++m) _Pragma("unroll") for (int n = 0; n < 2; ++n) _Pragma("unroll") for (int k = 0; k < 2; ++k) \
;         acc[ai][bj][m][n] = __builtin_amdgcn_mfma_f32_16x16x32_bf16(Bt[n][k], At[m][k], acc[ai][bj][m][n], 0, 0, 0); __builtin_amdgcn_s_setprio(0); } while (0)
; #define PG8_WAIT_V(n) asm volatile("s_waitcnt vmcnt(" #n ")" ::: "memory")
; #define PG8_WAIT_L(n) asm volatile("s_waitcnt lgkmcnt(" #n ")" ::: "memory")
; #define PG8_BAR __builtin_amdgcn_s_barrier()
; #define PG8_SCHED __builtin_amdgcn_sched_barrier(0)
; template <class Epi, class Sched, bool ALIGN_EPI = false, bool SP2 = false>
; __device__ __forceinline__ void gemm_phase(PG8_LAS unsigned char* lds, const Gemm g, const Sched& S, const Epi& E, int wid0) {
;     ...
;             PG8_WAIT_V(8); PG8_WAIT_L(0); PG8_BAR; PG8_MMA(1, 0, At, B0); PG8_MMA(1, 1, At, B1); PG8_BAR; PG8_SCHED;
;             PG8_LDB(B0, 1, 0); PG8_LDB(B1, 1, 1); PG8_SCHED; PG8_LDA(At, 1, 0); PG8_STAGE(PG8_SA(0, 1), a2 + hstep, voffA);
;             PG8_WAIT_V(8); PG8_WAIT_L(0); PG8_BAR; PG8_MMA(0, 0, At, B0); PG8_MMA(0, 1, At, B1); PG8_BAR; PG8_SCHED;
;             PG8_LDA(At, 1, 1); PG8_STAGE(PG8_SB(1, 0), b3, voffB); PG8_STAGE(PG8_SB(1, 1), b3 + hstep, voffB); PG8_STAGE(PG8_SA(1, 0), a3, voffA);
	s_setprio 1
	s_waitcnt lgkmcnt(0)
	v_mfma_f32_16x16x32_bf16 v[60:63], v[138:141], v[176:179], v[60:63]
	v_mfma_f32_16x16x32_bf16 v[56:59], v[152:155], v[176:179], v[56:59]
	v_mfma_f32_16x16x32_bf16 v[44:47], v[138:141], v[184:187], v[44:47]
	v_mfma_f32_16x16x32_bf16 v[40:43], v[152:155], v[184:187], v[40:43]
	v_mfma_f32_16x16x32_bf16 v[28:31], v[138:141], v[194:197], v[28:31]
	v_mfma_f32_16x16x32_bf16 v[24:27], v[152:155], v[194:197], v[24:27]
	v_mfma_f32_16x16x32_bf16 v[12:15], v[138:141], v[202:205], v[12:15]
	v_mfma_f32_16x16x32_bf16 v[8:11], v[152:155], v[202:205], v[8:11]
	v_mfma_f32_16x16x32_bf16 v[60:63], v[148:151], v[180:183], v[60:63]
	v_mfma_f32_16x16x32_bf16 v[56:59], v[156:159], v[180:183], v[56:59]
	v_mfma_f32_16x16x32_bf16 v[44:47], v[148:151], v[188:191], v[44:47]
	v_mfma_f32_16x16x32_bf16 v[40:43], v[156:159], v[188:191], v[40:43]
	v_mfma_f32_16x16x32_bf16 v[28:31], v[148:151], v[198:201], v[28:31]
	v_mfma_f32_16x16x32_bf16 v[24:27], v[156:159], v[198:201], v[24:27]
	v_mfma_f32_16x16x32_bf16 v[12:15], v[148:151], v[206:209], v[12:15]
	v_mfma_f32_16x16x32_bf16 v[8:11], v[156:159], v[206:209], v[8:11]
	s_setprio 0
	s_setprio 1
	v_mfma_f32_16x16x32_bf16 v[52:55], v[160:163], v[176:179], v[52:55]
	v_mfma_f32_16x16x32_bf16 v[48:51], v[168:171], v[176:179], v[48:51]
	v_mfma_f32_16x16x32_bf16 v[36:39], v[160:163], v[184:187], v[36:39]
	v_mfma_f32_16x16x32_bf16 v[32:35], v[168:171], v[184:187], v[32:35]
	v_mfma_f32_16x16x32_bf16 v[20:23], v[160:163], v[194:197], v[20:23]
	v_mfma_f32_16x16x32_bf16 v[16:19], v[168:171], v[194:197], v[16:19]
	v_mfma_f32_16x16x32_bf16 v[4:7], v[160:163], v[202:205], v[4:7]
	v_mfma_f32_16x16x32_bf16 v[0:3], v[168:171], v[202:205], v[0:3]
	v_mfma_f32_16x16x32_bf16 v[52:55], v[164:167], v[180:183], v[52:55]
	v_mfma_f32_16x16x32_bf16 v[48:51], v[172:175], v[180:183], v[48:51]
	v_mfma_f32_16x16x32_bf16 v[36:39], v[164:167], v[188:191], v[36:39]
	v_mfma_f32_16x16x32_bf16 v[32:35], v[172:175], v[188:191], v[32:35]
	v_mfma_f32_16x16x32_bf16 v[20:23], v[164:167], v[198:201], v[20:23]
	v_mfma_f32_16x16x32_bf16 v[16:19], v[172:175], v[198:201], v[16:19]
	v_mfma_f32_16x16x32_bf16 v[4:7], v[164:167], v[206:209], v[4:7]
	v_mfma_f32_16x16x32_bf16 v[0:3], v[172:175], v[206:209], v[0:3]
	s_barrier
	s_setprio 0
	s_add_i32 s65, 0, 0x18000
	s_add_i32 s66, 0, 0x1c000
	v_add_u32_e32 v156, s65, v143
	v_add_u32_e32 v172, s66, v143
	ds_read_b128 v[138:141], v156
	ds_read_b128 v[148:151], v156 offset:1024
	ds_read_b128 v[152:155], v156 offset:2048
	ds_read_b128 v[156:159], v156 offset:3072
	ds_read_b128 v[160:163], v172
	ds_read_b128 v[164:167], v172 offset:1024
	ds_read_b128 v[168:171], v172 offset:2048
	ds_read_b128 v[172:175], v172 offset:3072
	s_add_u32 s26, vcc_lo, 0x40000
	s_addc_u32 s27, vcc_hi, 0
	s_mov_b32 m0, s89
	v_lshl_add_u64 v[222:223], s[26:27], 0, v[128:129]
	ds_read_b128 v[176:179], v147 offset:32768
	ds_read_b128 v[180:183], v147 offset:33792
	ds_read_b128 v[184:187], v147 offset:34816
	ds_read_b128 v[188:191], v147 offset:35840
	ds_read_b128 v[194:197], v147 offset:36864
	ds_read_b128 v[198:201], v147 offset:37888
	ds_read_b128 v[202:205], v147 offset:38912
	ds_read_b128 v[206:209], v147 offset:39936
	global_load_lds_dwordx4 v[222:223], off
	v_lshl_add_u64 v[222:223], s[26:27], 0, v[130:131]
	s_mov_b32 m0, s90
	s_nop 0
	global_load_lds_dwordx4 v[222:223], off
	s_waitcnt vmcnt(8)
	s_waitcnt lgkmcnt(0)
	s_barrier
	s_setprio 1
	s_waitcnt lgkmcnt(0)
	v_mfma_f32_16x16x32_bf16 v[124:127], v[138:141], v[176:179], v[124:127]
	v_mfma_f32_16x16x32_bf16 v[120:123], v[152:155], v[176:179], v[120:123]
	v_mfma_f32_16x16x32_bf16 v[108:111], v[138:141], v[184:187], v[108:111]
	v_mfma_f32_16x16x32_bf16 v[104:107], v[152:155], v[184:187], v[104:107]
	v_mfma_f32_16x16x32_bf16 v[92:95], v[138:141], v[194:197], v[92:95]
	v_mfma_f32_16x16x32_bf16 v[88:91], v[152:155], v[194:197], v[88:91]
	v_mfma_f32_16x16x32_bf16 v[76:79], v[138:141], v[202:205], v[76:79]
	v_mfma_f32_16x16x32_bf16 v[72:75], v[152:155], v[202:205], v[72:75]
	v_mfma_f32_16x16x32_bf16 v[124:127], v[148:151], v[180:183], v[124:127]
	v_mfma_f32_16x16x32_bf16 v[120:123], v[156:159], v[180:183], v[120:123]
	v_mfma_f32_16x16x32_bf16 v[108:111], v[148:151], v[188:191], v[108:111]
	v_mfma_f32_16x16x32_bf16 v[104:107], v[156:159], v[188:191], v[104:107]
	v_mfma_f32_16x16x32_bf16 v[92:95], v[148:151], v[198:201], v[92:95]
	v_mfma_f32_16x16x32_bf16 v[88:91], v[156:159], v[198:201], v[88:91]
	v_mfma_f32_16x16x32_bf16 v[76:79], v[148:151], v[206:209], v[76:79]
	v_mfma_f32_16x16x32_bf16 v[72:75], v[156:159], v[206:209], v[72:75]
	s_setprio 0
	s_setprio 1
	v_mfma_f32_16x16x32_bf16 v[116:119], v[160:163], v[176:179], v[116:119]
	v_mfma_f32_16x16x32_bf16 v[112:115], v[168:171], v[176:179], v[112:115]
	v_mfma_f32_16x16x32_bf16 v[100:103], v[160:163], v[184:187], v[100:103]
	v_mfma_f32_16x16x32_bf16 v[96:99], v[168:171], v[184:187], v[96:99]
	v_mfma_f32_16x16x32_bf16 v[84:87], v[160:163], v[194:197], v[84:87]
	v_mfma_f32_16x16x32_bf16 v[80:83], v[168:171], v[194:197], v[80:83]
	v_mfma_f32_16x16x32_bf16 v[68:71], v[160:163], v[202:205], v[68:71]
	v_mfma_f32_16x16x32_bf16 v[64:67], v[168:171], v[202:205], v[64:67]
	v_mfma_f32_16x16x32_bf16 v[116:119], v[164:167], v[180:183], v[116:119]
	v_mfma_f32_16x16x32_bf16 v[112:115], v[172:175], v[180:183], v[112:115]
	v_mfma_f32_16x16x32_bf16 v[100:103], v[164:167], v[188:191], v[100:103]
	v_mfma_f32_16x16x32_bf16 v[96:99], v[172:175], v[188:191], v[96:99]
	v_mfma_f32_16x16x32_bf16 v[84:87], v[164:167], v[198:201], v[84:87]
	v_mfma_f32_16x16x32_bf16 v[80:83], v[172:175], v[198:201], v[80:83]
	v_mfma_f32_16x16x32_bf16 v[68:71], v[164:167], v[206:209], v[68:71]
	v_mfma_f32_16x16x32_bf16 v[64:67], v[172:175], v[206:209], v[64:67]
	s_barrier
; #define PG8_STAGE(bufoff, gbase, voff) do { _Pragma("unroll") for (int _i = 0; _i < 2; ++_i) \
;         __builtin_amdgcn_global_load_lds((const unsigned*)((const char*)(gbase) + (voff)[_i]), (PG8_LAS unsigned*)(lds + (bufoff) + ldsw + _i * 8192), 16, 0, 0); } while (0)
; #define PG8_LDA(dst, b, h) do { _Pragma("unroll") for (int m = 0; m < 4; ++m) _Pragma("unroll") for (int k = 0; k < 2; ++k) dst[m][k] = *(const PG8_LAS bf16x8*)(lds + PG8_SA(b, h) + aoff + m * 2048 + k * 1024); } while (0)
; #define PG8_MMA(ai, bj, At, Bt) do { __builtin_amdgcn_s_setprio(1); _Pragma("unroll") for (int m = 0; m < 4; ++m) _Pragma("unroll") for (int n = 0; n < 2; ++n) _Pragma("unroll") for (int k = 0; k < 2; ++k) \
;         acc[ai][bj][m][n] = __builtin_amdgcn_mfma_f32_16x16x32_bf16(Bt[n][k], At[m][k], acc[ai][bj][m][n], 0, 0, 0); __builtin_amdgcn_s_setprio(0); } while (0)
; #define PG8_WAIT_V(n) asm volatile("s_waitcnt vmcnt(" #n ")" ::: "memory")
; #define PG8_WAIT_L(n) asm volatile("s_waitcnt lgkmcnt(" #n ")" ::: "memory")
; #define PG8_BAR __builtin_amdgcn_s_barrier()
; #define PG8_SCHED __builtin_amdgcn_sched_barrier(0)
; template <class Epi, class Sched, bool ALIGN_EPI = false, bool SP2 = false>
; __device__ __forceinline__ void gemm_phase(PG8_LAS unsigned char* lds, const Gemm g, const Sched& S, const Epi& E, int wid0) {
;     ...
;             PG8_WAIT_V(8); PG8_WAIT_L(0); PG8_BAR; PG8_MMA(0, 0, At, B0); PG8_MMA(0, 1, At, B1); PG8_BAR; PG8_SCHED;
;             PG8_LDA(At, 1, 1); PG8_STAGE(PG8_SB(1, 0), b3, voffB); PG8_STAGE(PG8_SB(1, 1), b3 + hstep, voffB); PG8_STAGE(PG8_SA(1, 0), a3, voffA);
;             PG8_WAIT_V(8); PG8_WAIT_L(0); PG8_BAR; PG8_MMA(1, 0, At, B0); PG8_MMA(1, 1, At, B1); PG8_BAR; PG8_SCHED;
	s_setprio 0
	s_add_i32 s26, s65, s69
	v_lshl_add_u64 v[210:211], v[210:211], 0, s[30:31]
	s_mov_b32 m0, s26
	ds_read_b128 v[176:179], v147 offset:49152
	ds_read_b128 v[180:183], v147 offset:50176
	ds_read_b128 v[184:187], v147 offset:51200
	ds_read_b128 v[188:191], v147 offset:52224
	ds_read_b128 v[194:197], v147 offset:53248
	ds_read_b128 v[198:201], v147 offset:54272
	ds_read_b128 v[202:205], v147 offset:55296
	ds_read_b128 v[206:209], v147 offset:56320
	global_load_lds_dwordx4 v[210:211], off
	s_add_i32 m0, s26, 0x2000
	s_add_u32 s26, s76, 0x40080
	v_lshl_add_u64 v[210:211], v[212:213], 0, s[30:31]
	s_addc_u32 s27, s77, 0
	s_add_i32 s65, s66, s69
	global_load_lds_dwordx4 v[210:211], off
	v_lshl_add_u64 v[210:211], s[26:27], 0, v[192:193]
	s_mov_b32 m0, s65
	s_nop 0
	global_load_lds_dwordx4 v[210:211], off
	v_lshl_add_u64 v[210:211], s[26:27], 0, v[132:133]
	s_add_i32 m0, s65, 0x2000
	s_nop 0
	global_load_lds_dwordx4 v[210:211], off
	v_lshl_add_u64 v[210:211], v[214:215], 0, s[30:31]
	s_mov_b32 m0, s92
	s_nop 0
	global_load_lds_dwordx4 v[210:211], off
	v_lshl_add_u64 v[210:211], v[220:221], 0, s[30:31]
	s_mov_b32 m0, s93
	s_nop 0
	global_load_lds_dwordx4 v[210:211], off
	s_waitcnt vmcnt(8)
	s_waitcnt lgkmcnt(0)
	s_barrier
	s_setprio 1
	s_waitcnt lgkmcnt(0)
	v_mfma_f32_16x16x32_bf16 v[60:63], v[138:141], v[176:179], v[60:63]
	v_mfma_f32_16x16x32_bf16 v[56:59], v[152:155], v[176:179], v[56:59]
	v_mfma_f32_16x16x32_bf16 v[44:47], v[138:141], v[184:187], v[44:47]
	v_mfma_f32_16x16x32_bf16 v[40:43], v[152:155], v[184:187], v[40:43]
	v_mfma_f32_16x16x32_bf16 v[28:31], v[138:141], v[194:197], v[28:31]
	v_mfma_f32_16x16x32_bf16 v[24:27], v[152:155], v[194:197], v[24:27]
	v_mfma_f32_16x16x32_bf16 v[12:15], v[138:141], v[202:205], v[12:15]
	v_mfma_f32_16x16x32_bf16 v[8:11], v[152:155], v[202:205], v[8:11]
	v_mfma_f32_16x16x32_bf16 v[60:63], v[148:151], v[180:183], v[60:63]
	v_mfma_f32_16x16x32_bf16 v[56:59], v[156:159], v[180:183], v[56:59]
	v_mfma_f32_16x16x32_bf16 v[44:47], v[148:151], v[188:191], v[44:47]
	v_mfma_f32_16x16x32_bf16 v[40:43], v[156:159], v[188:191], v[40:43]
	v_mfma_f32_16x16x32_bf16 v[28:31], v[148:151], v[198:201], v[28:31]
	v_mfma_f32_16x16x32_bf16 v[24:27], v[156:159], v[198:201], v[24:27]
	v_mfma_f32_16x16x32_bf16 v[12:15], v[148:151], v[206:209], v[12:15]
	v_mfma_f32_16x16x32_bf16 v[8:11], v[156:159], v[206:209], v[8:11]
	s_setprio 0
	s_setprio 1
	v_mfma_f32_16x16x32_bf16 v[52:55], v[160:163], v[176:179], v[52:55]
	v_mfma_f32_16x16x32_bf16 v[48:51], v[168:171], v[176:179], v[48:51]
	v_mfma_f32_16x16x32_bf16 v[36:39], v[160:163], v[184:187], v[36:39]
	v_mfma_f32_16x16x32_bf16 v[32:35], v[168:171], v[184:187], v[32:35]
	v_mfma_f32_16x16x32_bf16 v[20:23], v[160:163], v[194:197], v[20:23]
	v_mfma_f32_16x16x32_bf16 v[16:19], v[168:171], v[194:197], v[16:19]
	v_mfma_f32_16x16x32_bf16 v[4:7], v[160:163], v[202:205], v[4:7]
	v_mfma_f32_16x16x32_bf16 v[0:3], v[168:171], v[202:205], v[0:3]
	v_mfma_f32_16x16x32_bf16 v[52:55], v[164:167], v[180:183], v[52:55]
	v_mfma_f32_16x16x32_bf16 v[48:51], v[172:175], v[180:183], v[48:51]
	v_mfma_f32_16x16x32_bf16 v[36:39], v[164:167], v[188:191], v[36:39]
	v_mfma_f32_16x16x32_bf16 v[32:35], v[172:175], v[188:191], v[32:35]
	v_mfma_f32_16x16x32_bf16 v[20:23], v[164:167], v[198:201], v[20:23]
	v_mfma_f32_16x16x32_bf16 v[16:19], v[172:175], v[198:201], v[16:19]
	v_mfma_f32_16x16x32_bf16 v[4:7], v[164:167], v[206:209], v[4:7]
	v_mfma_f32_16x16x32_bf16 v[0:3], v[172:175], v[206:209], v[0:3]
	s_barrier
	s_setprio 0
	s_add_i32 s64, s64, 2
	s_add_u32 s10, s10, 0x100
	s_addc_u32 s11, s11, 0
	s_add_u32 s84, s84, 0x100
	s_addc_u32 s85, s85, 0
	s_cmp_gt_u32 s64, 13
	s_cbranch_scc0 .LBB0_377
	s_and_b64 vcc, exec, s[70:71]
	s_cbranch_vccz .LBB0_380
	s_barrier

; #define PG8_STAGE(bufoff, gbase, voff) do { _Pragma("unroll") for (int _i = 0; _i < 2; ++_i) \
;         __builtin_amdgcn_global_load_lds((const unsigned*)((const char*)(gbase) + (voff)[_i]), (PG8_LAS unsigned*)(lds + (bufoff) + ldsw + _i * 8192), 16, 0, 0); } while (0)
; #define PG8_LDA(dst, b, h) do { _Pragma("unroll") for (int m = 0; m < 4; ++m) _Pragma("unroll") for (int k = 0; k < 2; ++k) dst[m][k] = *(const PG8_LAS bf16x8*)(lds + PG8_SA(b, h) + aoff + m * 2048 + k * 1024); } while (0)
; #define PG8_LDB(dst, b, h) do { _Pragma("unroll") for (int n = 0; n < 2; ++n) _Pragma("unroll") for (int k = 0; k < 2; ++k) dst[n][k] = *(const PG8_LAS bf16x8*)(lds + PG8_SB(b, h) + boff + n * 2048 + k * 1024); } while (0)
; #define PG8_MMA(ai, bj, At, Bt) do { __builtin_amdgcn_s_setprio(1); _Pragma("unroll") for (int m = 0; m < 4; ++m) _Pragma("unroll") for (int n = 0; n < 2; ++n) _Pragma("unroll") for (int k = 0; k < 2; ++k) \
;         acc[ai][bj][m][n] = __builtin_amdgcn_mfma_f32_16x16x32_bf16(Bt[n][k], At[m][k], acc[ai][bj][m][n], 0, 0, 0); __builtin_amdgcn_s_setprio(0); } while (0)
; #define PG8_WAIT_V(n) asm volatile("s_waitcnt vmcnt(" #n ")" ::: "memory")
; #define PG8_BAR __builtin_amdgcn_s_barrier()
; template <class Epi, class Sched, bool ALIGN_EPI = false, bool SP2 = false>
; __device__ __forceinline__ void gemm_phase(PG8_LAS unsigned char* lds, const Gemm g, const Sched& S, const Epi& E, int wid0) {
;     ...
;         for (int t = 0; t < nt; t += 2) {
;             const bool last = (t == nt - 2);
;             const char* a1 = cA + (size_t)(t + 1) * kstep;
;             const char* a2 = last ? nA : cA + (size_t)(t + 2) * kstep; const char* b2 = last ? nB : cB + (size_t)(t + 2) * kstep;
;             const char* a3 = a2 + kstep; const char* b3 = b2 + kstep;
;             if (last && has_next) S.a_ready(nxt);
;             if constexpr (SP2) {
;             PG8_LDB(B0, 0, 0); PG8_LDB(B1, 0, 1); PG8_SCHED; PG8_LDA(At, 0, 0); PG8_STAGE(PG8_SA(1, 1), a1 + hstep, voffA);
;             PG8_WAIT_V(8); PG8_WAIT_L(0); PG8_BAR; PG8_MMA(0, 0, At, B0); PG8_MMA(0, 1, At, B1); PG8_BAR; PG8_SCHED;
;             PG8_LDA(At, 0, 1); PG8_STAGE(PG8_SB(0, 0), b2, voffB); PG8_STAGE(PG8_SB(0, 1), b2 + hstep, voffB); PG8_STAGE(PG8_SA(0, 0), a2, voffA);
;             PG8_WAIT_V(8); PG8_WAIT_L(0); PG8_BAR; PG8_MMA(1, 0, At, B0); PG8_MMA(1, 1, At, B1); PG8_BAR; PG8_SCHED;
.LBB0_544:
	s_add_u32 s26, s80, 0xfffc0080
	s_addc_u32 s27, s81, -1
	s_add_i32 s65, 0, 0x10000
	s_cmp_eq_u32 s64, 12
	s_cselect_b32 s85, s45, s27
	s_cselect_b32 s84, s73, s26
	v_add_u32_e32 v142, s65, v146
	s_cselect_b32 s83, s71, s11
	s_cselect_b32 s82, s79, s10
	s_add_i32 s66, 0, 0x14000
	ds_read_b128 v[138:141], v142
	ds_read_b128 v[150:153], v142 offset:1024
	ds_read_b128 v[154:157], v142 offset:2048
	ds_read_b128 v[158:161], v142 offset:3072
	v_add_u32_e32 v142, s66, v146
	ds_read_b128 v[162:165], v142
	ds_read_b128 v[166:169], v142 offset:1024
	ds_read_b128 v[170:173], v142 offset:2048
	ds_read_b128 v[174:177], v142 offset:3072
	v_lshl_add_u64 v[142:143], s[80:81], 0, v[136:137]
	s_add_i32 m0, s87, 0xc000
	ds_read_b128 v[178:181], v148
	ds_read_b128 v[182:185], v148 offset:1024
	ds_read_b128 v[186:189], v148 offset:2048
	ds_read_b128 v[194:197], v148 offset:3072
	ds_read_b128 v[198:201], v148 offset:4096
	ds_read_b128 v[202:205], v148 offset:5120
	ds_read_b128 v[206:209], v148 offset:6144
	ds_read_b128 v[210:213], v148 offset:7168
	global_load_lds_dwordx4 v[142:143], off
	v_lshl_add_u64 v[142:143], s[80:81], 0, v[134:135]
	s_add_i32 m0, s87, 0xe000
	s_nop 0
	global_load_lds_dwordx4 v[142:143], off
	s_waitcnt vmcnt(8)
	s_waitcnt lgkmcnt(0)
	s_barrier
	s_setprio 1
	s_waitcnt lgkmcnt(0)
	v_mfma_f32_16x16x32_bf16 v[124:127], v[138:141], v[178:181], v[124:127]
	v_mfma_f32_16x16x32_bf16 v[116:119], v[154:157], v[178:181], v[116:119]
	v_mfma_f32_16x16x32_bf16 v[108:111], v[138:141], v[186:189], v[108:111]
	v_mfma_f32_16x16x32_bf16 v[100:103], v[154:157], v[186:189], v[100:103]
	v_mfma_f32_16x16x32_bf16 v[92:95], v[138:141], v[198:201], v[92:95]
	v_mfma_f32_16x16x32_bf16 v[84:87], v[154:157], v[198:201], v[84:87]
	v_mfma_f32_16x16x32_bf16 v[76:79], v[138:141], v[206:209], v[76:79]
	v_mfma_f32_16x16x32_bf16 v[68:71], v[154:157], v[206:209], v[68:71]
	v_mfma_f32_16x16x32_bf16 v[124:127], v[150:153], v[182:185], v[124:127]
	v_mfma_f32_16x16x32_bf16 v[116:119], v[158:161], v[182:185], v[116:119]
	v_mfma_f32_16x16x32_bf16 v[108:111], v[150:153], v[194:197], v[108:111]
	v_mfma_f32_16x16x32_bf16 v[100:103], v[158:161], v[194:197], v[100:103]
	v_mfma_f32_16x16x32_bf16 v[92:95], v[150:153], v[202:205], v[92:95]
	v_mfma_f32_16x16x32_bf16 v[84:87], v[158:161], v[202:205], v[84:87]
	v_mfma_f32_16x16x32_bf16 v[76:79], v[150:153], v[210:213], v[76:79]
	v_mfma_f32_16x16x32_bf16 v[68:71], v[158:161], v[210:213], v[68:71]
	s_setprio 0
	s_setprio 1
	v_mfma_f32_16x16x32_bf16 v[120:123], v[162:165], v[178:181], v[120:123]
	v_mfma_f32_16x16x32_bf16 v[112:115], v[170:173], v[178:181], v[112:115]
	v_mfma_f32_16x16x32_bf16 v[104:107], v[162:165], v[186:189], v[104:107]
	v_mfma_f32_16x16x32_bf16 v[96:99], v[170:173], v[186:189], v[96:99]
	v_mfma_f32_16x16x32_bf16 v[88:91], v[162:165], v[198:201], v[88:91]
	v_mfma_f32_16x16x32_bf16 v[80:83], v[170:173], v[198:201], v[80:83]
	v_mfma_f32_16x16x32_bf16 v[72:75], v[162:165], v[206:209], v[72:75]
	v_mfma_f32_16x16x32_bf16 v[64:67], v[170:173], v[206:209], v[64:67]
	v_mfma_f32_16x16x32_bf16 v[120:123], v[166:169], v[182:185], v[120:123]
	v_mfma_f32_16x16x32_bf16 v[112:115], v[174:177], v[182:185], v[112:115]
	v_mfma_f32_16x16x32_bf16 v[104:107], v[166:169], v[194:197], v[104:107]
	v_mfma_f32_16x16x32_bf16 v[96:99], v[174:177], v[194:197], v[96:99]
	v_mfma_f32_16x16x32_bf16 v[88:91], v[166:169], v[202:205], v[88:91]
	v_mfma_f32_16x16x32_bf16 v[80:83], v[174:177], v[202:205], v[80:83]
	v_mfma_f32_16x16x32_bf16 v[72:75], v[166:169], v[210:213], v[72:75]
	v_mfma_f32_16x16x32_bf16 v[64:67], v[174:177], v[210:213], v[64:67]
	s_barrier
	s_setprio 0
	s_add_i32 s26, s65, s86
	v_lshl_add_u64 v[142:143], s[82:83], 0, v[192:193]
	s_mov_b32 m0, s26
	ds_read_b128 v[178:181], v148 offset:16384
	ds_read_b128 v[182:185], v148 offset:17408
	ds_read_b128 v[186:189], v148 offset:18432
	ds_read_b128 v[194:197], v148 offset:19456
	ds_read_b128 v[198:201], v148 offset:20480
	ds_read_b128 v[202:205], v148 offset:21504
	ds_read_b128 v[206:209], v148 offset:22528
	ds_read_b128 v[210:213], v148 offset:23552
	global_load_lds_dwordx4 v[142:143], off
	s_add_i32 m0, s26, 0x2000
	s_add_u32 s26, s82, 0x40000
	v_lshl_add_u64 v[190:191], s[82:83], 0, v[128:129]
	s_addc_u32 s27, s83, 0
	s_add_i32 s65, s66, s86
	global_load_lds_dwordx4 v[190:191], off
	v_lshl_add_u64 v[214:215], s[26:27], 0, v[192:193]
	s_mov_b32 m0, s65
	v_lshl_add_u64 v[220:221], s[84:85], 0, v[130:131]
	global_load_lds_dwordx4 v[214:215], off
	v_lshl_add_u64 v[214:215], s[26:27], 0, v[128:129]
	s_add_i32 m0, s65, 0x2000
	s_nop 0
	global_load_lds_dwordx4 v[214:215], off
	v_lshl_add_u64 v[214:215], s[84:85], 0, v[132:133]
	s_mov_b32 m0, s87
	s_nop 0
	global_load_lds_dwordx4 v[214:215], off
	s_mov_b32 m0, s88
	s_nop 0
	global_load_lds_dwordx4 v[220:221], off
	s_waitcnt vmcnt(8)
	s_waitcnt lgkmcnt(0)
	s_barrier
; #define PG8_STAGE(bufoff, gbase, voff) do { _Pragma("unroll") for (int _i = 0; _i < 2; ++_i) \
;         __builtin_amdgcn_global_load_lds((const unsigned*)((const char*)(gbase) + (voff)[_i]), (PG8_LAS unsigned*)(lds + (bufoff) + ldsw + _i * 8192), 16, 0, 0); } while (0)
; #define PG8_LDA(dst, b, h) do { _Pragma("unroll") for (int m = 0; m < 4; ++m) _Pragma("unroll") for (int k = 0; k < 2; ++k) dst[m][k] = *(const PG8_LAS bf16x8*)(lds + PG8_SA(b, h) + aoff + m * 2048 + k * 1024); } while (0)
; #define PG8_LDB(dst, b, h) do { _Pragma("unroll") for (int n = 0; n < 2; ++n) _Pragma("unroll") for (int k = 0; k < 2; ++k) dst[n][k] = *(const PG8_LAS bf16x8*)(lds + PG8_SB(b, h) + boff + n * 2048 + k * 1024); } while (0)
; #define PG8_MMA(ai, bj, At, Bt) do { __builtin_amdgcn_s_setprio(1); _Pragma("unroll") for (int m = 0; m < 4; ++m) _Pragma("unroll") for (int n = 0; n < 2; ++n) _Pragma("unroll") for (int k = 0; k < 2; ++k) \
;         acc[ai][bj][m][n] = __builtin_amdgcn_mfma_f32_16x16x32_bf16(Bt[n][k], At[m][k], acc[ai][bj][m][n], 0, 0, 0); __builtin_amdgcn_s_setprio(0); } while (0)
; #define PG8_WAIT_V(n) asm volatile("s_waitcnt vmcnt(" #n ")" ::: "memory")
; #define PG8_WAIT_L(n) asm volatile("s_waitcnt lgkmcnt(" #n ")" ::: "memory")
; #define PG8_BAR __builtin_amdgcn_s_barrier()
; #define PG8_SCHED __builtin_amdgcn_sched_barrier(0)
; template <class Epi, class Sched, bool ALIGN_EPI = false, bool SP2 = false>
; __device__ __forceinline__ void gemm_phase(PG8_LAS unsigned char* lds, const Gemm g, const Sched& S, const Epi& E, int wid0) {
;     ...
;             PG8_WAIT_V(8); PG8_WAIT_L(0); PG8_BAR; PG8_MMA(1, 0, At, B0); PG8_MMA(1, 1, At, B1); PG8_BAR; PG8_SCHED;
;             PG8_LDB(B0, 1, 0); PG8_LDB(B1, 1, 1); PG8_SCHED; PG8_LDA(At, 1, 0); PG8_STAGE(PG8_SA(0, 1), a2 + hstep, voffA);
;             PG8_WAIT_V(8); PG8_WAIT_L(0); PG8_BAR; PG8_MMA(0, 0, At, B0); PG8_MMA(0, 1, At, B1); PG8_BAR; PG8_SCHED;
;             PG8_LDA(At, 1, 1); PG8_STAGE(PG8_SB(1, 0), b3, voffB); PG8_STAGE(PG8_SB(1, 1), b3 + hstep, voffB); PG8_STAGE(PG8_SA(1, 0), a3, voffA);
	s_setprio 1
	s_waitcnt lgkmcnt(0)
	v_mfma_f32_16x16x32_bf16 v[60:63], v[138:141], v[178:181], v[60:63]
	v_mfma_f32_16x16x32_bf16 v[52:55], v[154:157], v[178:181], v[52:55]
	v_mfma_f32_16x16x32_bf16 v[44:47], v[138:141], v[186:189], v[44:47]
	v_mfma_f32_16x16x32_bf16 v[36:39], v[154:157], v[186:189], v[36:39]
	v_mfma_f32_16x16x32_bf16 v[28:31], v[138:141], v[198:201], v[28:31]
	v_mfma_f32_16x16x32_bf16 v[20:23], v[154:157], v[198:201], v[20:23]
	v_mfma_f32_16x16x32_bf16 v[12:15], v[138:141], v[206:209], v[12:15]
	v_mfma_f32_16x16x32_bf16 v[4:7], v[154:157], v[206:209], v[4:7]
	v_mfma_f32_16x16x32_bf16 v[60:63], v[150:153], v[182:185], v[60:63]
	v_mfma_f32_16x16x32_bf16 v[52:55], v[158:161], v[182:185], v[52:55]
	v_mfma_f32_16x16x32_bf16 v[44:47], v[150:153], v[194:197], v[44:47]
	v_mfma_f32_16x16x32_bf16 v[36:39], v[158:161], v[194:197], v[36:39]
	v_mfma_f32_16x16x32_bf16 v[28:31], v[150:153], v[202:205], v[28:31]
	v_mfma_f32_16x16x32_bf16 v[20:23], v[158:161], v[202:205], v[20:23]
	v_mfma_f32_16x16x32_bf16 v[12:15], v[150:153], v[210:213], v[12:15]
	v_mfma_f32_16x16x32_bf16 v[4:7], v[158:161], v[210:213], v[4:7]
	s_setprio 0
	s_setprio 1
	v_mfma_f32_16x16x32_bf16 v[56:59], v[162:165], v[178:181], v[56:59]
	v_mfma_f32_16x16x32_bf16 v[48:51], v[170:173], v[178:181], v[48:51]
	v_mfma_f32_16x16x32_bf16 v[40:43], v[162:165], v[186:189], v[40:43]
	v_mfma_f32_16x16x32_bf16 v[32:35], v[170:173], v[186:189], v[32:35]
	v_mfma_f32_16x16x32_bf16 v[24:27], v[162:165], v[198:201], v[24:27]
	v_mfma_f32_16x16x32_bf16 v[16:19], v[170:173], v[198:201], v[16:19]
	v_mfma_f32_16x16x32_bf16 v[8:11], v[162:165], v[206:209], v[8:11]
	v_mfma_f32_16x16x32_bf16 v[0:3], v[170:173], v[206:209], v[0:3]
	v_mfma_f32_16x16x32_bf16 v[56:59], v[166:169], v[182:185], v[56:59]
	v_mfma_f32_16x16x32_bf16 v[48:51], v[174:177], v[182:185], v[48:51]
	v_mfma_f32_16x16x32_bf16 v[40:43], v[166:169], v[194:197], v[40:43]
	v_mfma_f32_16x16x32_bf16 v[32:35], v[174:177], v[194:197], v[32:35]
	v_mfma_f32_16x16x32_bf16 v[24:27], v[166:169], v[202:205], v[24:27]
	v_mfma_f32_16x16x32_bf16 v[16:19], v[174:177], v[202:205], v[16:19]
	v_mfma_f32_16x16x32_bf16 v[8:11], v[166:169], v[210:213], v[8:11]
	v_mfma_f32_16x16x32_bf16 v[0:3], v[174:177], v[210:213], v[0:3]
	s_barrier
	s_setprio 0
	s_add_i32 s65, 0, 0x18000
	v_add_u32_e32 v144, s65, v146
	s_add_i32 s66, 0, 0x1c000
	ds_read_b128 v[138:141], v144
	ds_read_b128 v[150:153], v144 offset:1024
	ds_read_b128 v[154:157], v144 offset:2048
	ds_read_b128 v[158:161], v144 offset:3072
	v_add_u32_e32 v144, s66, v146
	ds_read_b128 v[162:165], v144
	ds_read_b128 v[166:169], v144 offset:1024
	ds_read_b128 v[170:173], v144 offset:2048
	ds_read_b128 v[174:177], v144 offset:3072
	s_add_u32 s26, s84, 0x40000
	s_addc_u32 s27, s85, 0
	s_mov_b32 m0, s89
	v_lshl_add_u64 v[222:223], s[26:27], 0, v[132:133]
	ds_read_b128 v[178:181], v148 offset:32768
	ds_read_b128 v[182:185], v148 offset:33792
	ds_read_b128 v[186:189], v148 offset:34816
	ds_read_b128 v[194:197], v148 offset:35840
	ds_read_b128 v[198:201], v148 offset:36864
	ds_read_b128 v[202:205], v148 offset:37888
	ds_read_b128 v[206:209], v148 offset:38912
	ds_read_b128 v[210:213], v148 offset:39936
	global_load_lds_dwordx4 v[222:223], off
	v_lshl_add_u64 v[222:223], s[26:27], 0, v[130:131]
	s_mov_b32 m0, s90
	s_nop 0
	global_load_lds_dwordx4 v[222:223], off
	s_waitcnt vmcnt(8)
	s_waitcnt lgkmcnt(0)
	s_barrier
	s_setprio 1
	s_waitcnt lgkmcnt(0)
	v_mfma_f32_16x16x32_bf16 v[124:127], v[138:141], v[178:181], v[124:127]
	v_mfma_f32_16x16x32_bf16 v[116:119], v[154:157], v[178:181], v[116:119]
	v_mfma_f32_16x16x32_bf16 v[108:111], v[138:141], v[186:189], v[108:111]
	v_mfma_f32_16x16x32_bf16 v[100:103], v[154:157], v[186:189], v[100:103]
	v_mfma_f32_16x16x32_bf16 v[92:95], v[138:141], v[198:201], v[92:95]
	v_mfma_f32_16x16x32_bf16 v[84:87], v[154:157], v[198:201], v[84:87]
	v_mfma_f32_16x16x32_bf16 v[76:79], v[138:141], v[206:209], v[76:79]
	v_mfma_f32_16x16x32_bf16 v[68:71], v[154:157], v[206:209], v[68:71]
	v_mfma_f32_16x16x32_bf16 v[124:127], v[150:153], v[182:185], v[124:127]
	v_mfma_f32_16x16x32_bf16 v[116:119], v[158:161], v[182:185], v[116:119]
	v_mfma_f32_16x16x32_bf16 v[108:111], v[150:153], v[194:197], v[108:111]
	v_mfma_f32_16x16x32_bf16 v[100:103], v[158:161], v[194:197], v[100:103]
	v_mfma_f32_16x16x32_bf16 v[92:95], v[150:153], v[202:205], v[92:95]
	v_mfma_f32_16x16x32_bf16 v[84:87], v[158:161], v[202:205], v[84:87]
	v_mfma_f32_16x16x32_bf16 v[76:79], v[150:153], v[210:213], v[76:79]
	v_mfma_f32_16x16x32_bf16 v[68:71], v[158:161], v[210:213], v[68:71]
	s_setprio 0
	s_setprio 1
	v_mfma_f32_16x16x32_bf16 v[120:123], v[162:165], v[178:181], v[120:123]
	v_mfma_f32_16x16x32_bf16 v[112:115], v[170:173], v[178:181], v[112:115]
	v_mfma_f32_16x16x32_bf16 v[104:107], v[162:165], v[186:189], v[104:107]
	v_mfma_f32_16x16x32_bf16 v[96:99], v[170:173], v[186:189], v[96:99]
	v_mfma_f32_16x16x32_bf16 v[88:91], v[162:165], v[198:201], v[88:91]
	v_mfma_f32_16x16x32_bf16 v[80:83], v[170:173], v[198:201], v[80:83]
	v_mfma_f32_16x16x32_bf16 v[72:75], v[162:165], v[206:209], v[72:75]
	v_mfma_f32_16x16x32_bf16 v[64:67], v[170:173], v[206:209], v[64:67]
	v_mfma_f32_16x16x32_bf16 v[120:123], v[166:169], v[182:185], v[120:123]
	v_mfma_f32_16x16x32_bf16 v[112:115], v[174:177], v[182:185], v[112:115]
	v_mfma_f32_16x16x32_bf16 v[104:107], v[166:169], v[194:197], v[104:107]
	v_mfma_f32_16x16x32_bf16 v[96:99], v[174:177], v[194:197], v[96:99]
	v_mfma_f32_16x16x32_bf16 v[88:91], v[166:169], v[202:205], v[88:91]
	v_mfma_f32_16x16x32_bf16 v[80:83], v[174:177], v[202:205], v[80:83]
	v_mfma_f32_16x16x32_bf16 v[72:75], v[166:169], v[210:213], v[72:75]
	v_mfma_f32_16x16x32_bf16 v[64:67], v[174:177], v[210:213], v[64:67]
	s_barrier
; #define PG8_STAGE(bufoff, gbase, voff) do { _Pragma("unroll") for (int _i = 0; _i < 2; ++_i) \
;         __builtin_amdgcn_global_load_lds((const unsigned*)((const char*)(gbase) + (voff)[_i]), (PG8_LAS unsigned*)(lds + (bufoff) + ldsw + _i * 8192), 16, 0, 0); } while (0)
; #define PG8_LDA(dst, b, h) do { _Pragma("unroll") for (int m = 0; m < 4; ++m) _Pragma("unroll") for (int k = 0; k < 2; ++k) dst[m][k] = *(const PG8_LAS bf16x8*)(lds + PG8_SA(b, h) + aoff + m * 2048 + k * 1024); } while (0)
; #define PG8_MMA(ai, bj, At, Bt) do { __builtin_amdgcn_s_setprio(1); _Pragma("unroll") for (int m = 0; m < 4; ++m) _Pragma("unroll") for (int n = 0; n < 2; ++n) _Pragma("unroll") for (int k = 0; k < 2; ++k) \
;         acc[ai][bj][m][n] = __builtin_amdgcn_mfma_f32_16x16x32_bf16(Bt[n][k], At[m][k], acc[ai][bj][m][n], 0, 0, 0); __builtin_amdgcn_s_setprio(0); } while (0)
; #define PG8_WAIT_V(n) asm volatile("s_waitcnt vmcnt(" #n ")" ::: "memory")
; #define PG8_WAIT_L(n) asm volatile("s_waitcnt lgkmcnt(" #n ")" ::: "memory")
; #define PG8_BAR __builtin_amdgcn_s_barrier()
; #define PG8_SCHED __builtin_amdgcn_sched_barrier(0)
; template <class Epi, class Sched, bool ALIGN_EPI = false, bool SP2 = false>
; __device__ __forceinline__ void gemm_phase(PG8_LAS unsigned char* lds, const Gemm g, const Sched& S, const Epi& E, int wid0) {
;     ...
;             PG8_WAIT_V(8); PG8_WAIT_L(0); PG8_BAR; PG8_MMA(0, 0, At, B0); PG8_MMA(0, 1, At, B1); PG8_BAR; PG8_SCHED;
;             PG8_LDA(At, 1, 1); PG8_STAGE(PG8_SB(1, 0), b3, voffB); PG8_STAGE(PG8_SB(1, 1), b3 + hstep, voffB); PG8_STAGE(PG8_SA(1, 0), a3, voffA);
;             PG8_WAIT_V(8); PG8_WAIT_L(0); PG8_BAR; PG8_MMA(1, 0, At, B0); PG8_MMA(1, 1, At, B1); PG8_BAR; PG8_SCHED;
	s_setprio 0
	s_add_i32 s26, s65, s86
	v_lshl_add_u64 v[142:143], v[142:143], 0, s[30:31]
	s_mov_b32 m0, s26
	ds_read_b128 v[178:181], v148 offset:49152
	ds_read_b128 v[182:185], v148 offset:50176
	ds_read_b128 v[186:189], v148 offset:51200
	ds_read_b128 v[194:197], v148 offset:52224
	ds_read_b128 v[198:201], v148 offset:53248
	ds_read_b128 v[202:205], v148 offset:54272
	ds_read_b128 v[206:209], v148 offset:55296
	ds_read_b128 v[210:213], v148 offset:56320
	global_load_lds_dwordx4 v[142:143], off
	s_add_i32 m0, s26, 0x2000
	s_add_u32 s26, s82, 0x40080
	v_lshl_add_u64 v[142:143], v[190:191], 0, s[30:31]
	s_addc_u32 s27, s83, 0
	s_add_i32 s65, s66, s86
	global_load_lds_dwordx4 v[142:143], off
	v_lshl_add_u64 v[142:143], s[26:27], 0, v[192:193]
	s_mov_b32 m0, s65
	s_nop 0
	global_load_lds_dwordx4 v[142:143], off
	v_lshl_add_u64 v[142:143], s[26:27], 0, v[128:129]
	s_add_i32 m0, s65, 0x2000
	s_nop 0
	global_load_lds_dwordx4 v[142:143], off
	v_lshl_add_u64 v[142:143], v[214:215], 0, s[30:31]
	s_mov_b32 m0, s91
	s_nop 0
	global_load_lds_dwordx4 v[142:143], off
	v_lshl_add_u64 v[142:143], v[220:221], 0, s[30:31]
	s_mov_b32 m0, s92
	s_nop 0
	global_load_lds_dwordx4 v[142:143], off
	s_waitcnt vmcnt(8)
	s_waitcnt lgkmcnt(0)
	s_barrier
	s_setprio 1
	s_waitcnt lgkmcnt(0)
	v_mfma_f32_16x16x32_bf16 v[60:63], v[138:141], v[178:181], v[60:63]
	v_mfma_f32_16x16x32_bf16 v[52:55], v[154:157], v[178:181], v[52:55]
	v_mfma_f32_16x16x32_bf16 v[44:47], v[138:141], v[186:189], v[44:47]
	v_mfma_f32_16x16x32_bf16 v[36:39], v[154:157], v[186:189], v[36:39]
	v_mfma_f32_16x16x32_bf16 v[28:31], v[138:141], v[198:201], v[28:31]
	v_mfma_f32_16x16x32_bf16 v[20:23], v[154:157], v[198:201], v[20:23]
	v_mfma_f32_16x16x32_bf16 v[12:15], v[138:141], v[206:209], v[12:15]
	v_mfma_f32_16x16x32_bf16 v[4:7], v[154:157], v[206:209], v[4:7]
	v_mfma_f32_16x16x32_bf16 v[60:63], v[150:153], v[182:185], v[60:63]
	v_mfma_f32_16x16x32_bf16 v[52:55], v[158:161], v[182:185], v[52:55]
	v_mfma_f32_16x16x32_bf16 v[44:47], v[150:153], v[194:197], v[44:47]
	v_mfma_f32_16x16x32_bf16 v[36:39], v[158:161], v[194:197], v[36:39]
	v_mfma_f32_16x16x32_bf16 v[28:31], v[150:153], v[202:205], v[28:31]
	v_mfma_f32_16x16x32_bf16 v[20:23], v[158:161], v[202:205], v[20:23]
	v_mfma_f32_16x16x32_bf16 v[12:15], v[150:153], v[210:213], v[12:15]
	v_mfma_f32_16x16x32_bf16 v[4:7], v[158:161], v[210:213], v[4:7]
	s_setprio 0
	s_setprio 1
	v_mfma_f32_16x16x32_bf16 v[56:59], v[162:165], v[178:181], v[56:59]
	v_mfma_f32_16x16x32_bf16 v[48:51], v[170:173], v[178:181], v[48:51]
	v_mfma_f32_16x16x32_bf16 v[40:43], v[162:165], v[186:189], v[40:43]
	v_mfma_f32_16x16x32_bf16 v[32:35], v[170:173], v[186:189], v[32:35]
	v_mfma_f32_16x16x32_bf16 v[24:27], v[162:165], v[198:201], v[24:27]
	v_mfma_f32_16x16x32_bf16 v[16:19], v[170:173], v[198:201], v[16:19]
	v_mfma_f32_16x16x32_bf16 v[8:11], v[162:165], v[206:209], v[8:11]
	v_mfma_f32_16x16x32_bf16 v[0:3], v[170:173], v[206:209], v[0:3]
	v_mfma_f32_16x16x32_bf16 v[56:59], v[166:169], v[182:185], v[56:59]
	v_mfma_f32_16x16x32_bf16 v[48:51], v[174:177], v[182:185], v[48:51]
	v_mfma_f32_16x16x32_bf16 v[40:43], v[166:169], v[194:197], v[40:43]
	v_mfma_f32_16x16x32_bf16 v[32:35], v[174:177], v[194:197], v[32:35]
	v_mfma_f32_16x16x32_bf16 v[24:27], v[166:169], v[202:205], v[24:27]
	v_mfma_f32_16x16x32_bf16 v[16:19], v[174:177], v[202:205], v[16:19]
	v_mfma_f32_16x16x32_bf16 v[8:11], v[166:169], v[210:213], v[8:11]
	v_mfma_f32_16x16x32_bf16 v[0:3], v[174:177], v[210:213], v[0:3]
	s_barrier
	s_setprio 0
	s_add_i32 s64, s64, 2
	s_add_u32 s10, s10, 0x100
	s_addc_u32 s11, s11, 0
	s_add_u32 s80, s80, 0x100
	s_addc_u32 s81, s81, 0
	s_cmp_gt_u32 s64, 13
	s_cbranch_scc0 .LBB0_544
	s_and_b64 vcc, exec, s[42:43]
	s_cbranch_vccz .LBB0_547
	s_barrier

; #define PG8_STAGE(bufoff, gbase, voff) do { _Pragma("unroll") for (int _i = 0; _i < 2; ++_i) \
;         __builtin_amdgcn_global_load_lds((const unsigned*)((const char*)(gbase) + (voff)[_i]), (PG8_LAS unsigned*)(lds + (bufoff) + ldsw + _i * 8192), 16, 0, 0); } while (0)
; #define PG8_LDA(dst, b, h) do { _Pragma("unroll") for (int m = 0; m < 4; ++m) _Pragma("unroll") for (int k = 0; k < 2; ++k) dst[m][k] = *(const PG8_LAS bf16x8*)(lds + PG8_SA(b, h) + aoff + m * 2048 + k * 1024); } while (0)
; #define PG8_LDB(dst, b, h) do { _Pragma("unroll") for (int n = 0; n < 2; ++n) _Pragma("unroll") for (int k = 0; k < 2; ++k) dst[n][k] = *(const PG8_LAS bf16x8*)(lds + PG8_SB(b, h) + boff + n * 2048 + k * 1024); } while (0)
; #define PG8_MMA(ai, bj, At, Bt) do { __builtin_amdgcn_s_setprio(1); _Pragma("unroll") for (int m = 0; m < 4; ++m) _Pragma("unroll") for (int n = 0; n < 2; ++n) _Pragma("unroll") for (int k = 0; k < 2; ++k) \
;         acc[ai][bj][m][n] = __builtin_amdgcn_mfma_f32_16x16x32_bf16(Bt[n][k], At[m][k], acc[ai][bj][m][n], 0, 0, 0); __builtin_amdgcn_s_setprio(0); } while (0)
; #define PG8_WAIT_V(n) asm volatile("s_waitcnt vmcnt(" #n ")" ::: "memory")
; #define PG8_BAR __builtin_amdgcn_s_barrier()
; template <class Epi, class Sched, bool ALIGN_EPI = false, bool SP2 = false>
; __device__ __forceinline__ void gemm_phase(PG8_LAS unsigned char* lds, const Gemm g, const Sched& S, const Epi& E, int wid0) {
;     ...
;         for (int t = 0; t < nt; t += 2) {
;             const bool last = (t == nt - 2);
;             const char* a1 = cA + (size_t)(t + 1) * kstep;
;             const char* a2 = last ? nA : cA + (size_t)(t + 2) * kstep; const char* b2 = last ? nB : cB + (size_t)(t + 2) * kstep;
;             const char* a3 = a2 + kstep; const char* b3 = b2 + kstep;
;             if (last && has_next) S.a_ready(nxt);
;             if constexpr (SP2) {
;             PG8_LDB(B0, 0, 0); PG8_LDB(B1, 0, 1); PG8_SCHED; PG8_LDA(At, 0, 0); PG8_STAGE(PG8_SA(1, 1), a1 + hstep, voffA);
;             PG8_WAIT_V(8); PG8_WAIT_L(0); PG8_BAR; PG8_MMA(0, 0, At, B0); PG8_MMA(0, 1, At, B1); PG8_BAR; PG8_SCHED;
;             PG8_LDA(At, 0, 1); PG8_STAGE(PG8_SB(0, 0), b2, voffB); PG8_STAGE(PG8_SB(0, 1), b2 + hstep, voffB); PG8_STAGE(PG8_SA(0, 0), a2, voffA);
;             PG8_WAIT_V(8); PG8_WAIT_L(0); PG8_BAR; PG8_MMA(1, 0, At, B0); PG8_MMA(1, 1, At, B1); PG8_BAR; PG8_SCHED;
.LBB0_630:
	s_add_u32 s78, s76, 0x100
	s_addc_u32 s79, s77, 0
	s_add_i32 s26, 0, 0x10000
	s_cmp_eq_u32 s64, 40
	s_cselect_b32 s83, s43, s79
	s_cselect_b32 s82, s42, s78
	s_cselect_b32 s81, s75, s11
	s_cselect_b32 s80, s74, s10
	s_add_i32 s65, 0, 0x14000
	v_add_u32_e32 v156, s26, v143
	v_add_u32_e32 v172, s65, v143
	ds_read_b128 v[138:141], v156
	ds_read_b128 v[148:151], v156 offset:1024
	ds_read_b128 v[152:155], v156 offset:2048
	ds_read_b128 v[156:159], v156 offset:3072
	ds_read_b128 v[160:163], v172
	ds_read_b128 v[164:167], v172 offset:1024
	ds_read_b128 v[168:171], v172 offset:2048
	ds_read_b128 v[172:175], v172 offset:3072
	v_lshl_add_u64 v[210:211], s[76:77], 0, v[136:137]
	s_add_i32 m0, s84, 0xc000
	ds_read_b128 v[176:179], v147
	ds_read_b128 v[180:183], v147 offset:1024
	ds_read_b128 v[184:187], v147 offset:2048
	ds_read_b128 v[188:191], v147 offset:3072
	ds_read_b128 v[194:197], v147 offset:4096
	ds_read_b128 v[198:201], v147 offset:5120
	ds_read_b128 v[202:205], v147 offset:6144
	ds_read_b128 v[206:209], v147 offset:7168
	global_load_lds_dwordx4 v[210:211], off
	v_lshl_add_u64 v[210:211], s[76:77], 0, v[134:135]
	s_add_i32 m0, s84, 0xe000
	s_nop 0
	global_load_lds_dwordx4 v[210:211], off
	s_waitcnt vmcnt(8)
	s_waitcnt lgkmcnt(0)
	s_barrier
	s_setprio 1
	s_waitcnt lgkmcnt(0)
	v_mfma_f32_16x16x32_bf16 v[124:127], v[138:141], v[176:179], v[124:127]
	v_mfma_f32_16x16x32_bf16 v[120:123], v[152:155], v[176:179], v[120:123]
	v_mfma_f32_16x16x32_bf16 v[108:111], v[138:141], v[184:187], v[108:111]
	v_mfma_f32_16x16x32_bf16 v[104:107], v[152:155], v[184:187], v[104:107]
	v_mfma_f32_16x16x32_bf16 v[92:95], v[138:141], v[194:197], v[92:95]
	v_mfma_f32_16x16x32_bf16 v[88:91], v[152:155], v[194:197], v[88:91]
	v_mfma_f32_16x16x32_bf16 v[76:79], v[138:141], v[202:205], v[76:79]
	v_mfma_f32_16x16x32_bf16 v[72:75], v[152:155], v[202:205], v[72:75]
	v_mfma_f32_16x16x32_bf16 v[124:127], v[148:151], v[180:183], v[124:127]
	v_mfma_f32_16x16x32_bf16 v[120:123], v[156:159], v[180:183], v[120:123]
	v_mfma_f32_16x16x32_bf16 v[108:111], v[148:151], v[188:191], v[108:111]
	v_mfma_f32_16x16x32_bf16 v[104:107], v[156:159], v[188:191], v[104:107]
	v_mfma_f32_16x16x32_bf16 v[92:95], v[148:151], v[198:201], v[92:95]
	v_mfma_f32_16x16x32_bf16 v[88:91], v[156:159], v[198:201], v[88:91]
	v_mfma_f32_16x16x32_bf16 v[76:79], v[148:151], v[206:209], v[76:79]
	v_mfma_f32_16x16x32_bf16 v[72:75], v[156:159], v[206:209], v[72:75]
	s_setprio 0
	s_setprio 1
	v_mfma_f32_16x16x32_bf16 v[116:119], v[160:163], v[176:179], v[116:119]
	v_mfma_f32_16x16x32_bf16 v[112:115], v[168:171], v[176:179], v[112:115]
	v_mfma_f32_16x16x32_bf16 v[100:103], v[160:163], v[184:187], v[100:103]
	v_mfma_f32_16x16x32_bf16 v[96:99], v[168:171], v[184:187], v[96:99]
	v_mfma_f32_16x16x32_bf16 v[84:87], v[160:163], v[194:197], v[84:87]
	v_mfma_f32_16x16x32_bf16 v[80:83], v[168:171], v[194:197], v[80:83]
	v_mfma_f32_16x16x32_bf16 v[68:71], v[160:163], v[202:205], v[68:71]
	v_mfma_f32_16x16x32_bf16 v[64:67], v[168:171], v[202:205], v[64:67]
	v_mfma_f32_16x16x32_bf16 v[116:119], v[164:167], v[180:183], v[116:119]
	v_mfma_f32_16x16x32_bf16 v[112:115], v[172:175], v[180:183], v[112:115]
	v_mfma_f32_16x16x32_bf16 v[100:103], v[164:167], v[188:191], v[100:103]
	v_mfma_f32_16x16x32_bf16 v[96:99], v[172:175], v[188:191], v[96:99]
	v_mfma_f32_16x16x32_bf16 v[84:87], v[164:167], v[198:201], v[84:87]
	v_mfma_f32_16x16x32_bf16 v[80:83], v[172:175], v[198:201], v[80:83]
	v_mfma_f32_16x16x32_bf16 v[68:71], v[164:167], v[206:209], v[68:71]
	v_mfma_f32_16x16x32_bf16 v[64:67], v[172:175], v[206:209], v[64:67]
	s_barrier
	s_setprio 0
	s_add_i32 s26, s26, s69
	v_lshl_add_u64 v[210:211], s[80:81], 0, v[192:193]
	s_mov_b32 m0, s26
	ds_read_b128 v[176:179], v147 offset:16384
	ds_read_b128 v[180:183], v147 offset:17408
	ds_read_b128 v[184:187], v147 offset:18432
	ds_read_b128 v[188:191], v147 offset:19456
	ds_read_b128 v[194:197], v147 offset:20480
	ds_read_b128 v[198:201], v147 offset:21504
	ds_read_b128 v[202:205], v147 offset:22528
	ds_read_b128 v[206:209], v147 offset:23552
	global_load_lds_dwordx4 v[210:211], off
	s_add_i32 m0, s26, 0x2000
	s_add_u32 s26, s80, 0xb0000
	v_lshl_add_u64 v[212:213], s[80:81], 0, v[132:133]
	s_addc_u32 s27, s81, 0
	s_add_i32 s65, s65, s69
	global_load_lds_dwordx4 v[212:213], off
	v_lshl_add_u64 v[214:215], s[26:27], 0, v[192:193]
	s_mov_b32 m0, s65
	v_lshl_add_u64 v[220:221], s[82:83], 0, v[130:131]
	global_load_lds_dwordx4 v[214:215], off
	v_lshl_add_u64 v[214:215], s[26:27], 0, v[132:133]
	s_add_i32 m0, s65, 0x2000
	s_nop 0
	global_load_lds_dwordx4 v[214:215], off
	v_lshl_add_u64 v[214:215], s[82:83], 0, v[128:129]
	s_mov_b32 m0, s84
	s_nop 0
	global_load_lds_dwordx4 v[214:215], off
	s_mov_b32 m0, s85
	s_nop 0
	global_load_lds_dwordx4 v[220:221], off
	s_waitcnt vmcnt(8)
	s_waitcnt lgkmcnt(0)
	s_barrier
; #define PG8_STAGE(bufoff, gbase, voff) do { _Pragma("unroll") for (int _i = 0; _i < 2; ++_i) \
;         __builtin_amdgcn_global_load_lds((const unsigned*)((const char*)(gbase) + (voff)[_i]), (PG8_LAS unsigned*)(lds + (bufoff) + ldsw + _i * 8192), 16, 0, 0); } while (0)
; #define PG8_LDA(dst, b, h) do { _Pragma("unroll") for (int m = 0; m < 4; ++m) _Pragma("unroll") for (int k = 0; k < 2; ++k) dst[m][k] = *(const PG8_LAS bf16x8*)(lds + PG8_SA(b, h) + aoff + m * 2048 + k * 1024); } while (0)
; #define PG8_LDB(dst, b, h) do { _Pragma("unroll") for (int n = 0; n < 2; ++n) _Pragma("unroll") for (int k = 0; k < 2; ++k) dst[n][k] = *(const PG8_LAS bf16x8*)(lds + PG8_SB(b, h) + boff + n * 2048 + k * 1024); } while (0)
; #define PG8_MMA(ai, bj, At, Bt) do { __builtin_amdgcn_s_setprio(1); _Pragma("unroll") for (int m = 0; m < 4; ++m) _Pragma("unroll") for (int n = 0; n < 2; ++n) _Pragma("unroll") for (int k = 0; k < 2; ++k) \
;         acc[ai][bj][m][n] = __builtin_amdgcn_mfma_f32_16x16x32_bf16(Bt[n][k], At[m][k], acc[ai][bj][m][n], 0, 0, 0); __builtin_amdgcn_s_setprio(0); } while (0)
; #define PG8_WAIT_V(n) asm volatile("s_waitcnt vmcnt(" #n ")" ::: "memory")
; #define PG8_WAIT_L(n) asm volatile("s_waitcnt lgkmcnt(" #n ")" ::: "memory")
; #define PG8_BAR __builtin_amdgcn_s_barrier()
; #define PG8_SCHED __builtin_amdgcn_sched_barrier(0)
; template <class Epi, class Sched, bool ALIGN_EPI = false, bool SP2 = false>
; __device__ __forceinline__ void gemm_phase(PG8_LAS unsigned char* lds, const Gemm g, const Sched& S, const Epi& E, int wid0) {
;     ...
;             PG8_WAIT_V(8); PG8_WAIT_L(0); PG8_BAR; PG8_MMA(1, 0, At, B0); PG8_MMA(1, 1, At, B1); PG8_BAR; PG8_SCHED;
;             PG8_LDB(B0, 1, 0); PG8_LDB(B1, 1, 1); PG8_SCHED; PG8_LDA(At, 1, 0); PG8_STAGE(PG8_SA(0, 1), a2 + hstep, voffA);
;             PG8_WAIT_V(8); PG8_WAIT_L(0); PG8_BAR; PG8_MMA(0, 0, At, B0); PG8_MMA(0, 1, At, B1); PG8_BAR; PG8_SCHED;
;             PG8_LDA(At, 1, 1); PG8_STAGE(PG8_SB(1, 0), b3, voffB); PG8_STAGE(PG8_SB(1, 1), b3 + hstep, voffB); PG8_STAGE(PG8_SA(1, 0), a3, voffA);
	s_setprio 1
	s_waitcnt lgkmcnt(0)
	v_mfma_f32_16x16x32_bf16 v[60:63], v[138:141], v[176:179], v[60:63]
	v_mfma_f32_16x16x32_bf16 v[56:59], v[152:155], v[176:179], v[56:59]
	v_mfma_f32_16x16x32_bf16 v[44:47], v[138:141], v[184:187], v[44:47]
	v_mfma_f32_16x16x32_bf16 v[40:43], v[152:155], v[184:187], v[40:43]
	v_mfma_f32_16x16x32_bf16 v[28:31], v[138:141], v[194:197], v[28:31]
	v_mfma_f32_16x16x32_bf16 v[24:27], v[152:155], v[194:197], v[24:27]
	v_mfma_f32_16x16x32_bf16 v[12:15], v[138:141], v[202:205], v[12:15]
	v_mfma_f32_16x16x32_bf16 v[8:11], v[152:155], v[202:205], v[8:11]
	v_mfma_f32_16x16x32_bf16 v[60:63], v[148:151], v[180:183], v[60:63]
	v_mfma_f32_16x16x32_bf16 v[56:59], v[156:159], v[180:183], v[56:59]
	v_mfma_f32_16x16x32_bf16 v[44:47], v[148:151], v[188:191], v[44:47]
	v_mfma_f32_16x16x32_bf16 v[40:43], v[156:159], v[188:191], v[40:43]
	v_mfma_f32_16x16x32_bf16 v[28:31], v[148:151], v[198:201], v[28:31]
	v_mfma_f32_16x16x32_bf16 v[24:27], v[156:159], v[198:201], v[24:27]
	v_mfma_f32_16x16x32_bf16 v[12:15], v[148:151], v[206:209], v[12:15]
	v_mfma_f32_16x16x32_bf16 v[8:11], v[156:159], v[206:209], v[8:11]
	s_setprio 0
	s_setprio 1
	v_mfma_f32_16x16x32_bf16 v[52:55], v[160:163], v[176:179], v[52:55]
	v_mfma_f32_16x16x32_bf16 v[48:51], v[168:171], v[176:179], v[48:51]
	v_mfma_f32_16x16x32_bf16 v[36:39], v[160:163], v[184:187], v[36:39]
	v_mfma_f32_16x16x32_bf16 v[32:35], v[168:171], v[184:187], v[32:35]
	v_mfma_f32_16x16x32_bf16 v[20:23], v[160:163], v[194:197], v[20:23]
	v_mfma_f32_16x16x32_bf16 v[16:19], v[168:171], v[194:197], v[16:19]
	v_mfma_f32_16x16x32_bf16 v[4:7], v[160:163], v[202:205], v[4:7]
	v_mfma_f32_16x16x32_bf16 v[0:3], v[168:171], v[202:205], v[0:3]
	v_mfma_f32_16x16x32_bf16 v[52:55], v[164:167], v[180:183], v[52:55]
	v_mfma_f32_16x16x32_bf16 v[48:51], v[172:175], v[180:183], v[48:51]
	v_mfma_f32_16x16x32_bf16 v[36:39], v[164:167], v[188:191], v[36:39]
	v_mfma_f32_16x16x32_bf16 v[32:35], v[172:175], v[188:191], v[32:35]
	v_mfma_f32_16x16x32_bf16 v[20:23], v[164:167], v[198:201], v[20:23]
	v_mfma_f32_16x16x32_bf16 v[16:19], v[172:175], v[198:201], v[16:19]
	v_mfma_f32_16x16x32_bf16 v[4:7], v[164:167], v[206:209], v[4:7]
	v_mfma_f32_16x16x32_bf16 v[0:3], v[172:175], v[206:209], v[0:3]
	s_barrier
	s_setprio 0
	s_add_i32 s65, 0, 0x18000
	s_add_i32 s66, 0, 0x1c000
	v_add_u32_e32 v156, s65, v143
	v_add_u32_e32 v172, s66, v143
	ds_read_b128 v[138:141], v156
	ds_read_b128 v[148:151], v156 offset:1024
	ds_read_b128 v[152:155], v156 offset:2048
	ds_read_b128 v[156:159], v156 offset:3072
	ds_read_b128 v[160:163], v172
	ds_read_b128 v[164:167], v172 offset:1024
	ds_read_b128 v[168:171], v172 offset:2048
	ds_read_b128 v[172:175], v172 offset:3072
	s_add_u32 s26, s82, 0xb0000
	s_addc_u32 s27, s83, 0
	s_mov_b32 m0, s86
	v_lshl_add_u64 v[222:223], s[26:27], 0, v[128:129]
	ds_read_b128 v[176:179], v147 offset:32768
	ds_read_b128 v[180:183], v147 offset:33792
	ds_read_b128 v[184:187], v147 offset:34816
	ds_read_b128 v[188:191], v147 offset:35840
	ds_read_b128 v[194:197], v147 offset:36864
	ds_read_b128 v[198:201], v147 offset:37888
	ds_read_b128 v[202:205], v147 offset:38912
	ds_read_b128 v[206:209], v147 offset:39936
	global_load_lds_dwordx4 v[222:223], off
	v_lshl_add_u64 v[222:223], s[26:27], 0, v[130:131]
	s_mov_b32 m0, s87
	s_nop 0
	global_load_lds_dwordx4 v[222:223], off
	s_waitcnt vmcnt(8)
	s_waitcnt lgkmcnt(0)
	s_barrier
	s_setprio 1
	s_waitcnt lgkmcnt(0)
	v_mfma_f32_16x16x32_bf16 v[124:127], v[138:141], v[176:179], v[124:127]
	v_mfma_f32_16x16x32_bf16 v[120:123], v[152:155], v[176:179], v[120:123]
	v_mfma_f32_16x16x32_bf16 v[108:111], v[138:141], v[184:187], v[108:111]
	v_mfma_f32_16x16x32_bf16 v[104:107], v[152:155], v[184:187], v[104:107]
	v_mfma_f32_16x16x32_bf16 v[92:95], v[138:141], v[194:197], v[92:95]
	v_mfma_f32_16x16x32_bf16 v[88:91], v[152:155], v[194:197], v[88:91]
	v_mfma_f32_16x16x32_bf16 v[76:79], v[138:141], v[202:205], v[76:79]
	v_mfma_f32_16x16x32_bf16 v[72:75], v[152:155], v[202:205], v[72:75]
	v_mfma_f32_16x16x32_bf16 v[124:127], v[148:151], v[180:183], v[124:127]
	v_mfma_f32_16x16x32_bf16 v[120:123], v[156:159], v[180:183], v[120:123]
	v_mfma_f32_16x16x32_bf16 v[108:111], v[148:151], v[188:191], v[108:111]
	v_mfma_f32_16x16x32_bf16 v[104:107], v[156:159], v[188:191], v[104:107]
	v_mfma_f32_16x16x32_bf16 v[92:95], v[148:151], v[198:201], v[92:95]
	v_mfma_f32_16x16x32_bf16 v[88:91], v[156:159], v[198:201], v[88:91]
	v_mfma_f32_16x16x32_bf16 v[76:79], v[148:151], v[206:209], v[76:79]
	v_mfma_f32_16x16x32_bf16 v[72:75], v[156:159], v[206:209], v[72:75]
	s_setprio 0
	s_setprio 1
	v_mfma_f32_16x16x32_bf16 v[116:119], v[160:163], v[176:179], v[116:119]
	v_mfma_f32_16x16x32_bf16 v[112:115], v[168:171], v[176:179], v[112:115]
	v_mfma_f32_16x16x32_bf16 v[100:103], v[160:163], v[184:187], v[100:103]
	v_mfma_f32_16x16x32_bf16 v[96:99], v[168:171], v[184:187], v[96:99]
	v_mfma_f32_16x16x32_bf16 v[84:87], v[160:163], v[194:197], v[84:87]
	v_mfma_f32_16x16x32_bf16 v[80:83], v[168:171], v[194:197], v[80:83]
	v_mfma_f32_16x16x32_bf16 v[68:71], v[160:163], v[202:205], v[68:71]
	v_mfma_f32_16x16x32_bf16 v[64:67], v[168:171], v[202:205], v[64:67]
	v_mfma_f32_16x16x32_bf16 v[116:119], v[164:167], v[180:183], v[116:119]
	v_mfma_f32_16x16x32_bf16 v[112:115], v[172:175], v[180:183], v[112:115]
	v_mfma_f32_16x16x32_bf16 v[100:103], v[164:167], v[188:191], v[100:103]
	v_mfma_f32_16x16x32_bf16 v[96:99], v[172:175], v[188:191], v[96:99]
	v_mfma_f32_16x16x32_bf16 v[84:87], v[164:167], v[198:201], v[84:87]
	v_mfma_f32_16x16x32_bf16 v[80:83], v[172:175], v[198:201], v[80:83]
	v_mfma_f32_16x16x32_bf16 v[68:71], v[164:167], v[206:209], v[68:71]
	v_mfma_f32_16x16x32_bf16 v[64:67], v[172:175], v[206:209], v[64:67]
	s_barrier
; #define PG8_STAGE(bufoff, gbase, voff) do { _Pragma("unroll") for (int _i = 0; _i < 2; ++_i) \
;         __builtin_amdgcn_global_load_lds((const unsigned*)((const char*)(gbase) + (voff)[_i]), (PG8_LAS unsigned*)(lds + (bufoff) + ldsw + _i * 8192), 16, 0, 0); } while (0)
; #define PG8_LDA(dst, b, h) do { _Pragma("unroll") for (int m = 0; m < 4; ++m) _Pragma("unroll") for (int k = 0; k < 2; ++k) dst[m][k] = *(const PG8_LAS bf16x8*)(lds + PG8_SA(b, h) + aoff + m * 2048 + k * 1024); } while (0)
; #define PG8_MMA(ai, bj, At, Bt) do { __builtin_amdgcn_s_setprio(1); _Pragma("unroll") for (int m = 0; m < 4; ++m) _Pragma("unroll") for (int n = 0; n < 2; ++n) _Pragma("unroll") for (int k = 0; k < 2; ++k) \
;         acc[ai][bj][m][n] = __builtin_amdgcn_mfma_f32_16x16x32_bf16(Bt[n][k], At[m][k], acc[ai][bj][m][n], 0, 0, 0); __builtin_amdgcn_s_setprio(0); } while (0)
; #define PG8_WAIT_V(n) asm volatile("s_waitcnt vmcnt(" #n ")" ::: "memory")
; #define PG8_WAIT_L(n) asm volatile("s_waitcnt lgkmcnt(" #n ")" ::: "memory")
; #define PG8_BAR __builtin_amdgcn_s_barrier()
; #define PG8_SCHED __builtin_amdgcn_sched_barrier(0)
; template <class Epi, class Sched, bool ALIGN_EPI = false, bool SP2 = false>
; __device__ __forceinline__ void gemm_phase(PG8_LAS unsigned char* lds, const Gemm g, const Sched& S, const Epi& E, int wid0) {
;     ...
;             PG8_WAIT_V(8); PG8_WAIT_L(0); PG8_BAR; PG8_MMA(0, 0, At, B0); PG8_MMA(0, 1, At, B1); PG8_BAR; PG8_SCHED;
;             PG8_LDA(At, 1, 1); PG8_STAGE(PG8_SB(1, 0), b3, voffB); PG8_STAGE(PG8_SB(1, 1), b3 + hstep, voffB); PG8_STAGE(PG8_SA(1, 0), a3, voffA);
;             PG8_WAIT_V(8); PG8_WAIT_L(0); PG8_BAR; PG8_MMA(1, 0, At, B0); PG8_MMA(1, 1, At, B1); PG8_BAR; PG8_SCHED;
	s_setprio 0
	s_add_i32 s26, s65, s69
	v_lshl_add_u64 v[210:211], v[210:211], 0, s[30:31]
	s_mov_b32 m0, s26
	ds_read_b128 v[176:179], v147 offset:49152
	ds_read_b128 v[180:183], v147 offset:50176
	ds_read_b128 v[184:187], v147 offset:51200
	ds_read_b128 v[188:191], v147 offset:52224
	ds_read_b128 v[194:197], v147 offset:53248
	ds_read_b128 v[198:201], v147 offset:54272
	ds_read_b128 v[202:205], v147 offset:55296
	ds_read_b128 v[206:209], v147 offset:56320
	global_load_lds_dwordx4 v[210:211], off
	s_add_i32 m0, s26, 0x2000
	s_add_u32 s26, s80, 0xb0080
	v_lshl_add_u64 v[210:211], v[212:213], 0, s[30:31]
	s_addc_u32 s27, s81, 0
	s_add_i32 s65, s66, s69
	global_load_lds_dwordx4 v[210:211], off
	v_lshl_add_u64 v[210:211], s[26:27], 0, v[192:193]
	s_mov_b32 m0, s65
	s_nop 0
	global_load_lds_dwordx4 v[210:211], off
	v_lshl_add_u64 v[210:211], s[26:27], 0, v[132:133]
	s_add_i32 m0, s65, 0x2000
	s_nop 0
	global_load_lds_dwordx4 v[210:211], off
	v_lshl_add_u64 v[210:211], v[214:215], 0, s[30:31]
	s_mov_b32 m0, s89
	s_nop 0
	global_load_lds_dwordx4 v[210:211], off
	v_lshl_add_u64 v[210:211], v[220:221], 0, s[30:31]
	s_mov_b32 m0, s90
	s_nop 0
	global_load_lds_dwordx4 v[210:211], off
	s_waitcnt vmcnt(8)
	s_waitcnt lgkmcnt(0)
	s_barrier
	s_setprio 1
	s_waitcnt lgkmcnt(0)
	v_mfma_f32_16x16x32_bf16 v[60:63], v[138:141], v[176:179], v[60:63]
	v_mfma_f32_16x16x32_bf16 v[56:59], v[152:155], v[176:179], v[56:59]
	v_mfma_f32_16x16x32_bf16 v[44:47], v[138:141], v[184:187], v[44:47]
	v_mfma_f32_16x16x32_bf16 v[40:43], v[152:155], v[184:187], v[40:43]
	v_mfma_f32_16x16x32_bf16 v[28:31], v[138:141], v[194:197], v[28:31]
	v_mfma_f32_16x16x32_bf16 v[24:27], v[152:155], v[194:197], v[24:27]
	v_mfma_f32_16x16x32_bf16 v[12:15], v[138:141], v[202:205], v[12:15]
	v_mfma_f32_16x16x32_bf16 v[8:11], v[152:155], v[202:205], v[8:11]
	v_mfma_f32_16x16x32_bf16 v[60:63], v[148:151], v[180:183], v[60:63]
	v_mfma_f32_16x16x32_bf16 v[56:59], v[156:159], v[180:183], v[56:59]
	v_mfma_f32_16x16x32_bf16 v[44:47], v[148:151], v[188:191], v[44:47]
	v_mfma_f32_16x16x32_bf16 v[40:43], v[156:159], v[188:191], v[40:43]
	v_mfma_f32_16x16x32_bf16 v[28:31], v[148:151], v[198:201], v[28:31]
	v_mfma_f32_16x16x32_bf16 v[24:27], v[156:159], v[198:201], v[24:27]
	v_mfma_f32_16x16x32_bf16 v[12:15], v[148:151], v[206:209], v[12:15]
	v_mfma_f32_16x16x32_bf16 v[8:11], v[156:159], v[206:209], v[8:11]
	s_setprio 0
	s_setprio 1
	v_mfma_f32_16x16x32_bf16 v[52:55], v[160:163], v[176:179], v[52:55]
	v_mfma_f32_16x16x32_bf16 v[48:51], v[168:171], v[176:179], v[48:51]
	v_mfma_f32_16x16x32_bf16 v[36:39], v[160:163], v[184:187], v[36:39]
	v_mfma_f32_16x16x32_bf16 v[32:35], v[168:171], v[184:187], v[32:35]
	v_mfma_f32_16x16x32_bf16 v[20:23], v[160:163], v[194:197], v[20:23]
	v_mfma_f32_16x16x32_bf16 v[16:19], v[168:171], v[194:197], v[16:19]
	v_mfma_f32_16x16x32_bf16 v[4:7], v[160:163], v[202:205], v[4:7]
	v_mfma_f32_16x16x32_bf16 v[0:3], v[168:171], v[202:205], v[0:3]
	v_mfma_f32_16x16x32_bf16 v[52:55], v[164:167], v[180:183], v[52:55]
	v_mfma_f32_16x16x32_bf16 v[48:51], v[172:175], v[180:183], v[48:51]
	v_mfma_f32_16x16x32_bf16 v[36:39], v[164:167], v[188:191], v[36:39]
	v_mfma_f32_16x16x32_bf16 v[32:35], v[172:175], v[188:191], v[32:35]
	v_mfma_f32_16x16x32_bf16 v[20:23], v[164:167], v[198:201], v[20:23]
	v_mfma_f32_16x16x32_bf16 v[16:19], v[172:175], v[198:201], v[16:19]
	v_mfma_f32_16x16x32_bf16 v[4:7], v[164:167], v[206:209], v[4:7]
	v_mfma_f32_16x16x32_bf16 v[0:3], v[172:175], v[206:209], v[0:3]
	s_barrier
	s_setprio 0
	s_add_i32 s64, s64, 2
	s_add_u32 s10, s10, 0x100
	s_addc_u32 s11, s11, 0
	s_cmp_gt_u32 s64, 41
	s_mov_b64 s[76:77], s[78:79]
	s_cbranch_scc0 .LBB0_630
	s_and_b64 vcc, exec, s[72:73]
	s_cbranch_vccz .LBB0_633
	s_barrier
